# v10 + K-loop barrier turnaround tightened: setprio moved across barriers, redundant lgkmcnt(0) and mid-block flips removed
# speedup vs baseline: 1.0088x; 1.0055x over previous
; #define PG8_STAGE(bufoff, gbase, voff) do { _Pragma("unroll") for (int _i = 0; _i < 2; ++_i) \
;         __builtin_amdgcn_global_load_lds((const unsigned*)((const char*)(gbase) + (voff)[_i]), (PG8_LAS unsigned*)(lds + (bufoff) + ldsw + _i * 8192), 16, 0, 0); } while (0)
; #define PG8_LDA(dst, b, h) do { _Pragma("unroll") for (int m = 0; m < 4; ++m) _Pragma("unroll") for (int k = 0; k < 2; ++k) dst[m][k] = *(const PG8_LAS bf16x8*)(lds + PG8_SA(b, h) + aoff + m * 2048 + k * 1024); } while (0)
; #define PG8_LDB(dst, b, h) do { _Pragma("unroll") for (int n = 0; n < 2; ++n) _Pragma("unroll") for (int k = 0; k < 2; ++k) dst[n][k] = *(const PG8_LAS bf16x8*)(lds + PG8_SB(b, h) + boff + n * 2048 + k * 1024); } while (0)
; #define PG8_WAIT_V(n) asm volatile("s_waitcnt vmcnt(" #n ")" ::: "memory")
; #define PG8_WAIT_L(n) asm volatile("s_waitcnt lgkmcnt(" #n ")" ::: "memory")
; #define PG8_BAR __builtin_amdgcn_s_barrier()
; #define PG8_SCHED __builtin_amdgcn_sched_barrier(0)
; template <class Epi, class Sched, bool ALIGN_EPI = false, bool SP2 = false, bool F16 = false>
; __device__ __forceinline__ void gemm_phase(PG8_LAS unsigned char* lds, const Gemm g, const Sched& S, const Epi& E) {
;     ...
;         for (int t = 0; t < nt; t += 2) {
;             const bool last = (t == nt - 2);
;             const char* a1 = cA + (size_t)(t + 1) * kstep;
;             const char* a2 = last ? nA : cA + (size_t)(t + 2) * kstep; const char* b2 = last ? nB : cB + (size_t)(t + 2) * kstep;
;             const char* a3 = a2 + kstep; const char* b3 = b2 + kstep;
;             if (last && has_next) S.a_ready(nxt);
;             if constexpr (SP2) {
;             PG8_LDB(B0, 0, 0); PG8_LDB(B1, 0, 1); PG8_SCHED; PG8_LDA(At, 0, 0); PG8_STAGE(PG8_SA(1, 1), a1 + hstepA, voffA);
;             PG8_WAIT_V(8); PG8_WAIT_L(0); PG8_BAR; PG8_MMA(0, 0, At, B0); PG8_MMA(0, 1, At, B1); PG8_BAR; PG8_SCHED;
;             PG8_LDA(At, 0, 1); PG8_STAGE(PG8_SB(0, 0), b2, voffB); PG8_STAGE(PG8_SB(0, 1), b2 + hstepB, voffB); PG8_STAGE(PG8_SA(0, 0), a2, voffA);
;             PG8_WAIT_V(8); PG8_WAIT_L(0); PG8_BAR; PG8_MMA(1, 0, At, B0); PG8_MMA(1, 1, At, B1); PG8_BAR; PG8_SCHED;
.LBB0_310:
	s_add_i32 s82, s54, 2
	s_add_u32 s83, s52, 0x80
	s_addc_u32 s55, s53, 0
	s_add_i32 vcc_lo, 0, 0x10000
	s_cmp_eq_u32 s74, s54
	s_cselect_b32 s55, s39, s55
	s_cselect_b32 s54, s38, s83
	s_cselect_b32 s95, s47, s81
	s_cselect_b32 s94, s46, s80
	s_add_i32 s83, 0, 0x14000
	v_add_u32_e32 v156, vcc_lo, v165
	v_add_u32_e32 v164, s83, v165
	ds_read_b128 v[130:133], v156
	ds_read_b128 v[134:137], v156 offset:1024
	ds_read_b128 v[152:155], v156 offset:2048
	ds_read_b128 v[156:159], v156 offset:3072
	ds_read_b128 v[160:163], v164
	ds_read_b128 v[166:169], v164 offset:1024
	ds_read_b128 v[184:187], v164 offset:2048
	ds_read_b128 v[188:191], v164 offset:3072
	v_lshl_add_u64 v[172:173], s[52:53], 0, v[148:149]
	s_add_i32 m0, s22, 0xc000
	ds_read_b128 v[192:195], v183
	ds_read_b128 v[204:207], v183 offset:1024
	ds_read_b128 v[208:211], v183 offset:2048
	ds_read_b128 v[212:215], v183 offset:3072
	ds_read_b128 v[216:219], v183 offset:4096
	ds_read_b128 v[220:223], v183 offset:5120
	ds_read_b128 v[224:227], v183 offset:6144
	ds_read_b128 v[228:231], v183 offset:7168
	global_load_lds_dwordx4 v[172:173], off
	v_lshl_add_u64 v[172:173], s[52:53], 0, v[150:151]
	s_add_i32 m0, s22, 0xe000
	s_nop 0
	global_load_lds_dwordx4 v[172:173], off
	s_waitcnt vmcnt(8)
	s_waitcnt lgkmcnt(0)
	s_setprio 1
	s_barrier
	v_mfma_f32_16x16x32_f16 v[122:125], v[130:133], v[192:195], v[122:125]
	v_mfma_f32_16x16x32_f16 v[114:117], v[152:155], v[192:195], v[114:117]
	v_mfma_f32_16x16x32_f16 v[106:109], v[130:133], v[208:211], v[106:109]
	v_mfma_f32_16x16x32_f16 v[98:101], v[152:155], v[208:211], v[98:101]
	v_mfma_f32_16x16x32_f16 v[90:93], v[130:133], v[216:219], v[90:93]
	v_mfma_f32_16x16x32_f16 v[82:85], v[152:155], v[216:219], v[82:85]
	v_mfma_f32_16x16x32_f16 v[74:77], v[130:133], v[224:227], v[74:77]
	v_mfma_f32_16x16x32_f16 v[66:69], v[152:155], v[224:227], v[66:69]
	v_mfma_f32_16x16x32_f16 v[122:125], v[134:137], v[204:207], v[122:125]
	v_mfma_f32_16x16x32_f16 v[114:117], v[156:159], v[204:207], v[114:117]
	v_mfma_f32_16x16x32_f16 v[106:109], v[134:137], v[212:215], v[106:109]
	v_mfma_f32_16x16x32_f16 v[98:101], v[156:159], v[212:215], v[98:101]
	v_mfma_f32_16x16x32_f16 v[90:93], v[134:137], v[220:223], v[90:93]
	v_mfma_f32_16x16x32_f16 v[82:85], v[156:159], v[220:223], v[82:85]
	v_mfma_f32_16x16x32_f16 v[74:77], v[134:137], v[228:231], v[74:77]
	v_mfma_f32_16x16x32_f16 v[66:69], v[156:159], v[228:231], v[66:69]
	v_mfma_f32_16x16x32_f16 v[126:129], v[160:163], v[192:195], v[126:129]
	v_mfma_f32_16x16x32_f16 v[118:121], v[184:187], v[192:195], v[118:121]
	v_mfma_f32_16x16x32_f16 v[110:113], v[160:163], v[208:211], v[110:113]
	v_mfma_f32_16x16x32_f16 v[102:105], v[184:187], v[208:211], v[102:105]
	v_mfma_f32_16x16x32_f16 v[94:97], v[160:163], v[216:219], v[94:97]
	v_mfma_f32_16x16x32_f16 v[86:89], v[184:187], v[216:219], v[86:89]
	v_mfma_f32_16x16x32_f16 v[78:81], v[160:163], v[224:227], v[78:81]
	v_mfma_f32_16x16x32_f16 v[70:73], v[184:187], v[224:227], v[70:73]
	v_mfma_f32_16x16x32_f16 v[126:129], v[166:169], v[204:207], v[126:129]
	v_mfma_f32_16x16x32_f16 v[118:121], v[188:191], v[204:207], v[118:121]
	v_mfma_f32_16x16x32_f16 v[110:113], v[166:169], v[212:215], v[110:113]
	v_mfma_f32_16x16x32_f16 v[102:105], v[188:191], v[212:215], v[102:105]
	v_mfma_f32_16x16x32_f16 v[94:97], v[166:169], v[220:223], v[94:97]
	v_mfma_f32_16x16x32_f16 v[86:89], v[188:191], v[220:223], v[86:89]
	v_mfma_f32_16x16x32_f16 v[78:81], v[166:169], v[228:231], v[78:81]
	v_mfma_f32_16x16x32_f16 v[70:73], v[188:191], v[228:231], v[70:73]
	s_barrier
	s_setprio 0
	s_add_i32 vcc_lo, vcc_lo, s2
	v_lshl_add_u64 v[172:173], s[94:95], 0, v[142:143]
	s_mov_b32 m0, vcc_lo
	ds_read_b128 v[192:195], v183 offset:16384
	ds_read_b128 v[204:207], v183 offset:17408
	ds_read_b128 v[208:211], v183 offset:18432
	ds_read_b128 v[212:215], v183 offset:19456
	ds_read_b128 v[216:219], v183 offset:20480
	ds_read_b128 v[220:223], v183 offset:21504
	ds_read_b128 v[224:227], v183 offset:22528
	ds_read_b128 v[228:231], v183 offset:23552
	global_load_lds_dwordx4 v[172:173], off
	s_add_i32 m0, vcc_lo, 0x2000
	v_lshl_add_u64 v[176:177], s[94:95], 0, v[138:139]
	s_add_u32 s94, s94, s48
	s_addc_u32 s95, s95, 0
	s_add_i32 s83, s83, s2
	global_load_lds_dwordx4 v[176:177], off
	v_lshl_add_u64 v[196:197], s[94:95], 0, v[142:143]
	s_mov_b32 m0, s83
	v_lshl_add_u64 v[232:233], s[94:95], 0, v[138:139]
	global_load_lds_dwordx4 v[196:197], off
	s_add_i32 m0, s83, 0x2000
	v_lshl_add_u64 v[234:235], s[54:55], 0, v[144:145]
	global_load_lds_dwordx4 v[232:233], off
	s_mov_b32 m0, s22
	v_lshl_add_u64 v[236:237], s[54:55], 0, v[140:141]
	global_load_lds_dwordx4 v[234:235], off
	s_mov_b32 m0, s33
	s_nop 0
	global_load_lds_dwordx4 v[236:237], off
	s_waitcnt vmcnt(8)
	s_waitcnt lgkmcnt(0)
	s_setprio 1
	s_barrier
; #define PG8_STAGE(bufoff, gbase, voff) do { _Pragma("unroll") for (int _i = 0; _i < 2; ++_i) \
;         __builtin_amdgcn_global_load_lds((const unsigned*)((const char*)(gbase) + (voff)[_i]), (PG8_LAS unsigned*)(lds + (bufoff) + ldsw + _i * 8192), 16, 0, 0); } while (0)
; #define PG8_LDA(dst, b, h) do { _Pragma("unroll") for (int m = 0; m < 4; ++m) _Pragma("unroll") for (int k = 0; k < 2; ++k) dst[m][k] = *(const PG8_LAS bf16x8*)(lds + PG8_SA(b, h) + aoff + m * 2048 + k * 1024); } while (0)
; #define PG8_LDB(dst, b, h) do { _Pragma("unroll") for (int n = 0; n < 2; ++n) _Pragma("unroll") for (int k = 0; k < 2; ++k) dst[n][k] = *(const PG8_LAS bf16x8*)(lds + PG8_SB(b, h) + boff + n * 2048 + k * 1024); } while (0)
; #define PG8_WAIT_V(n) asm volatile("s_waitcnt vmcnt(" #n ")" ::: "memory")
; #define PG8_WAIT_L(n) asm volatile("s_waitcnt lgkmcnt(" #n ")" ::: "memory")
; #define PG8_BAR __builtin_amdgcn_s_barrier()
; #define PG8_SCHED __builtin_amdgcn_sched_barrier(0)
; template <class Epi, class Sched, bool ALIGN_EPI = false, bool SP2 = false, bool F16 = false>
; __device__ __forceinline__ void gemm_phase(PG8_LAS unsigned char* lds, const Gemm g, const Sched& S, const Epi& E) {
;     ...
;             PG8_WAIT_V(8); PG8_WAIT_L(0); PG8_BAR; PG8_MMA(1, 0, At, B0); PG8_MMA(1, 1, At, B1); PG8_BAR; PG8_SCHED;
;             PG8_LDB(B0, 1, 0); PG8_LDB(B1, 1, 1); PG8_SCHED; PG8_LDA(At, 1, 0); PG8_STAGE(PG8_SA(0, 1), a2 + hstepA, voffA);
;             PG8_WAIT_V(8); PG8_WAIT_L(0); PG8_BAR; PG8_MMA(0, 0, At, B0); PG8_MMA(0, 1, At, B1); PG8_BAR; PG8_SCHED;
	v_mfma_f32_16x16x32_f16 v[58:61], v[130:133], v[192:195], v[58:61]
	v_mfma_f32_16x16x32_f16 v[50:53], v[152:155], v[192:195], v[50:53]
	v_mfma_f32_16x16x32_f16 v[42:45], v[130:133], v[208:211], v[42:45]
	v_mfma_f32_16x16x32_f16 v[34:37], v[152:155], v[208:211], v[34:37]
	v_mfma_f32_16x16x32_f16 v[26:29], v[130:133], v[216:219], v[26:29]
	v_mfma_f32_16x16x32_f16 v[18:21], v[152:155], v[216:219], v[18:21]
	v_mfma_f32_16x16x32_f16 v[10:13], v[130:133], v[224:227], v[10:13]
	v_mfma_f32_16x16x32_f16 v[6:9], v[152:155], v[224:227], v[6:9]
	v_mfma_f32_16x16x32_f16 v[58:61], v[134:137], v[204:207], v[58:61]
	v_mfma_f32_16x16x32_f16 v[50:53], v[156:159], v[204:207], v[50:53]
	v_mfma_f32_16x16x32_f16 v[42:45], v[134:137], v[212:215], v[42:45]
	v_mfma_f32_16x16x32_f16 v[34:37], v[156:159], v[212:215], v[34:37]
	v_mfma_f32_16x16x32_f16 v[26:29], v[134:137], v[220:223], v[26:29]
	v_mfma_f32_16x16x32_f16 v[18:21], v[156:159], v[220:223], v[18:21]
	v_mfma_f32_16x16x32_f16 v[10:13], v[134:137], v[228:231], v[10:13]
	v_mfma_f32_16x16x32_f16 v[6:9], v[156:159], v[228:231], v[6:9]
	v_mfma_f32_16x16x32_f16 v[62:65], v[160:163], v[192:195], v[62:65]
	v_mfma_f32_16x16x32_f16 v[54:57], v[184:187], v[192:195], v[54:57]
	v_mfma_f32_16x16x32_f16 v[46:49], v[160:163], v[208:211], v[46:49]
	v_mfma_f32_16x16x32_f16 v[38:41], v[184:187], v[208:211], v[38:41]
	v_mfma_f32_16x16x32_f16 v[30:33], v[160:163], v[216:219], v[30:33]
	v_mfma_f32_16x16x32_f16 v[22:25], v[184:187], v[216:219], v[22:25]
	v_mfma_f32_16x16x32_f16 v[14:17], v[160:163], v[224:227], v[14:17]
	v_mfma_f32_16x16x32_f16 v[2:5], v[184:187], v[224:227], v[2:5]
	v_mfma_f32_16x16x32_f16 v[62:65], v[166:169], v[204:207], v[62:65]
	v_mfma_f32_16x16x32_f16 v[54:57], v[188:191], v[204:207], v[54:57]
	v_mfma_f32_16x16x32_f16 v[46:49], v[166:169], v[212:215], v[46:49]
	v_mfma_f32_16x16x32_f16 v[38:41], v[188:191], v[212:215], v[38:41]
	v_mfma_f32_16x16x32_f16 v[30:33], v[166:169], v[220:223], v[30:33]
	v_mfma_f32_16x16x32_f16 v[22:25], v[188:191], v[220:223], v[22:25]
	v_mfma_f32_16x16x32_f16 v[14:17], v[166:169], v[228:231], v[14:17]
	v_mfma_f32_16x16x32_f16 v[2:5], v[188:191], v[228:231], v[2:5]
	s_barrier
	s_setprio 0
	s_add_i32 s83, 0, 0x18000
	s_add_i32 s94, 0, 0x1c000
	v_add_u32_e32 v156, s83, v165
	v_add_u32_e32 v164, s94, v165
	ds_read_b128 v[130:133], v156
	ds_read_b128 v[134:137], v156 offset:1024
	ds_read_b128 v[152:155], v156 offset:2048
	ds_read_b128 v[156:159], v156 offset:3072
	ds_read_b128 v[160:163], v164
	ds_read_b128 v[166:169], v164 offset:1024
	ds_read_b128 v[184:187], v164 offset:2048
	ds_read_b128 v[188:191], v164 offset:3072
	s_add_u32 s54, s54, s8
	s_addc_u32 s55, s55, 0
	s_mov_b32 m0, s12
	v_lshl_add_u64 v[238:239], s[54:55], 0, v[144:145]
	ds_read_b128 v[192:195], v183 offset:32768
	ds_read_b128 v[204:207], v183 offset:33792
	ds_read_b128 v[208:211], v183 offset:34816
	ds_read_b128 v[212:215], v183 offset:35840
	ds_read_b128 v[216:219], v183 offset:36864
	ds_read_b128 v[220:223], v183 offset:37888
	ds_read_b128 v[224:227], v183 offset:38912
	ds_read_b128 v[228:231], v183 offset:39936
	global_load_lds_dwordx4 v[238:239], off
	v_lshl_add_u64 v[238:239], s[54:55], 0, v[140:141]
	s_mov_b32 m0, s13
	s_nop 0
	global_load_lds_dwordx4 v[238:239], off
	s_waitcnt vmcnt(8)
	s_waitcnt lgkmcnt(0)
	s_setprio 1
	s_barrier
	v_mfma_f32_16x16x32_f16 v[122:125], v[130:133], v[192:195], v[122:125]
	v_mfma_f32_16x16x32_f16 v[114:117], v[152:155], v[192:195], v[114:117]
	v_mfma_f32_16x16x32_f16 v[106:109], v[130:133], v[208:211], v[106:109]
	v_mfma_f32_16x16x32_f16 v[98:101], v[152:155], v[208:211], v[98:101]
	v_mfma_f32_16x16x32_f16 v[90:93], v[130:133], v[216:219], v[90:93]
	v_mfma_f32_16x16x32_f16 v[82:85], v[152:155], v[216:219], v[82:85]
	v_mfma_f32_16x16x32_f16 v[74:77], v[130:133], v[224:227], v[74:77]
	v_mfma_f32_16x16x32_f16 v[66:69], v[152:155], v[224:227], v[66:69]
	v_mfma_f32_16x16x32_f16 v[122:125], v[134:137], v[204:207], v[122:125]
	v_mfma_f32_16x16x32_f16 v[114:117], v[156:159], v[204:207], v[114:117]
	v_mfma_f32_16x16x32_f16 v[106:109], v[134:137], v[212:215], v[106:109]
	v_mfma_f32_16x16x32_f16 v[98:101], v[156:159], v[212:215], v[98:101]
	v_mfma_f32_16x16x32_f16 v[90:93], v[134:137], v[220:223], v[90:93]
	v_mfma_f32_16x16x32_f16 v[82:85], v[156:159], v[220:223], v[82:85]
	v_mfma_f32_16x16x32_f16 v[74:77], v[134:137], v[228:231], v[74:77]
	v_mfma_f32_16x16x32_f16 v[66:69], v[156:159], v[228:231], v[66:69]
	v_mfma_f32_16x16x32_f16 v[126:129], v[160:163], v[192:195], v[126:129]
	v_mfma_f32_16x16x32_f16 v[118:121], v[184:187], v[192:195], v[118:121]
	v_mfma_f32_16x16x32_f16 v[110:113], v[160:163], v[208:211], v[110:113]
	v_mfma_f32_16x16x32_f16 v[102:105], v[184:187], v[208:211], v[102:105]
	v_mfma_f32_16x16x32_f16 v[94:97], v[160:163], v[216:219], v[94:97]
	v_mfma_f32_16x16x32_f16 v[86:89], v[184:187], v[216:219], v[86:89]
	v_mfma_f32_16x16x32_f16 v[78:81], v[160:163], v[224:227], v[78:81]
	v_mfma_f32_16x16x32_f16 v[70:73], v[184:187], v[224:227], v[70:73]
	v_mfma_f32_16x16x32_f16 v[126:129], v[166:169], v[204:207], v[126:129]
	v_mfma_f32_16x16x32_f16 v[118:121], v[188:191], v[204:207], v[118:121]
	v_mfma_f32_16x16x32_f16 v[110:113], v[166:169], v[212:215], v[110:113]
	v_mfma_f32_16x16x32_f16 v[102:105], v[188:191], v[212:215], v[102:105]
	v_mfma_f32_16x16x32_f16 v[94:97], v[166:169], v[220:223], v[94:97]
	v_mfma_f32_16x16x32_f16 v[86:89], v[188:191], v[220:223], v[86:89]
	v_mfma_f32_16x16x32_f16 v[78:81], v[166:169], v[228:231], v[78:81]
	v_mfma_f32_16x16x32_f16 v[70:73], v[188:191], v[228:231], v[70:73]
	s_barrier
; #define PG8_STAGE(bufoff, gbase, voff) do { _Pragma("unroll") for (int _i = 0; _i < 2; ++_i) \
;         __builtin_amdgcn_global_load_lds((const unsigned*)((const char*)(gbase) + (voff)[_i]), (PG8_LAS unsigned*)(lds + (bufoff) + ldsw + _i * 8192), 16, 0, 0); } while (0)
; #define PG8_LDA(dst, b, h) do { _Pragma("unroll") for (int m = 0; m < 4; ++m) _Pragma("unroll") for (int k = 0; k < 2; ++k) dst[m][k] = *(const PG8_LAS bf16x8*)(lds + PG8_SA(b, h) + aoff + m * 2048 + k * 1024); } while (0)
; #define PG8_WAIT_V(n) asm volatile("s_waitcnt vmcnt(" #n ")" ::: "memory")
; #define PG8_WAIT_L(n) asm volatile("s_waitcnt lgkmcnt(" #n ")" ::: "memory")
; #define PG8_BAR __builtin_amdgcn_s_barrier()
; #define PG8_SCHED __builtin_amdgcn_sched_barrier(0)
; template <class Epi, class Sched, bool ALIGN_EPI = false, bool SP2 = false, bool F16 = false>
; __device__ __forceinline__ void gemm_phase(PG8_LAS unsigned char* lds, const Gemm g, const Sched& S, const Epi& E) {
;     ...
;             PG8_LDA(At, 1, 1); PG8_STAGE(PG8_SB(1, 0), b3, voffB); PG8_STAGE(PG8_SB(1, 1), b3 + hstepB, voffB); PG8_STAGE(PG8_SA(1, 0), a3, voffA);
;             PG8_WAIT_V(8); PG8_WAIT_L(0); PG8_BAR; PG8_MMA(1, 0, At, B0); PG8_MMA(1, 1, At, B1); PG8_BAR; PG8_SCHED;
	s_setprio 0
	s_add_i32 s54, s83, s2
	v_lshl_add_u64 v[172:173], v[172:173], 0, s[92:93]
	s_mov_b32 m0, s54
	ds_read_b128 v[192:195], v183 offset:49152
	ds_read_b128 v[204:207], v183 offset:50176
	ds_read_b128 v[208:211], v183 offset:51200
	ds_read_b128 v[212:215], v183 offset:52224
	ds_read_b128 v[216:219], v183 offset:53248
	ds_read_b128 v[220:223], v183 offset:54272
	ds_read_b128 v[224:227], v183 offset:55296
	ds_read_b128 v[228:231], v183 offset:56320
	global_load_lds_dwordx4 v[172:173], off
	v_lshl_add_u64 v[172:173], v[176:177], 0, s[92:93]
	s_add_i32 m0, s54, 0x2000
	s_add_i32 s54, s94, s2
	global_load_lds_dwordx4 v[172:173], off
	v_lshl_add_u64 v[172:173], v[196:197], 0, s[92:93]
	s_mov_b32 m0, s54
	s_nop 0
	global_load_lds_dwordx4 v[172:173], off
	v_lshl_add_u64 v[172:173], v[232:233], 0, s[92:93]
	s_add_i32 m0, s54, 0x2000
	s_nop 0
	global_load_lds_dwordx4 v[172:173], off
	v_lshl_add_u64 v[172:173], v[234:235], 0, s[92:93]
	s_mov_b32 m0, s35
	s_nop 0
	global_load_lds_dwordx4 v[172:173], off
	v_lshl_add_u64 v[172:173], v[236:237], 0, s[92:93]
	s_mov_b32 m0, s59
	s_nop 0
	global_load_lds_dwordx4 v[172:173], off
	s_waitcnt vmcnt(8)
	s_waitcnt lgkmcnt(0)
	s_setprio 1
	s_barrier
	v_mfma_f32_16x16x32_f16 v[58:61], v[130:133], v[192:195], v[58:61]
	v_mfma_f32_16x16x32_f16 v[50:53], v[152:155], v[192:195], v[50:53]
	v_mfma_f32_16x16x32_f16 v[42:45], v[130:133], v[208:211], v[42:45]
	v_mfma_f32_16x16x32_f16 v[34:37], v[152:155], v[208:211], v[34:37]
	v_mfma_f32_16x16x32_f16 v[26:29], v[130:133], v[216:219], v[26:29]
	v_mfma_f32_16x16x32_f16 v[18:21], v[152:155], v[216:219], v[18:21]
	v_mfma_f32_16x16x32_f16 v[10:13], v[130:133], v[224:227], v[10:13]
	v_mfma_f32_16x16x32_f16 v[6:9], v[152:155], v[224:227], v[6:9]
	v_mfma_f32_16x16x32_f16 v[58:61], v[134:137], v[204:207], v[58:61]
	v_mfma_f32_16x16x32_f16 v[50:53], v[156:159], v[204:207], v[50:53]
	v_mfma_f32_16x16x32_f16 v[42:45], v[134:137], v[212:215], v[42:45]
	v_mfma_f32_16x16x32_f16 v[34:37], v[156:159], v[212:215], v[34:37]
	v_mfma_f32_16x16x32_f16 v[26:29], v[134:137], v[220:223], v[26:29]
	v_mfma_f32_16x16x32_f16 v[18:21], v[156:159], v[220:223], v[18:21]
	v_mfma_f32_16x16x32_f16 v[10:13], v[134:137], v[228:231], v[10:13]
	v_mfma_f32_16x16x32_f16 v[6:9], v[156:159], v[228:231], v[6:9]
	v_mfma_f32_16x16x32_f16 v[62:65], v[160:163], v[192:195], v[62:65]
	v_mfma_f32_16x16x32_f16 v[54:57], v[184:187], v[192:195], v[54:57]
	v_mfma_f32_16x16x32_f16 v[46:49], v[160:163], v[208:211], v[46:49]
	v_mfma_f32_16x16x32_f16 v[38:41], v[184:187], v[208:211], v[38:41]
	v_mfma_f32_16x16x32_f16 v[30:33], v[160:163], v[216:219], v[30:33]
	v_mfma_f32_16x16x32_f16 v[22:25], v[184:187], v[216:219], v[22:25]
	v_mfma_f32_16x16x32_f16 v[14:17], v[160:163], v[224:227], v[14:17]
	v_mfma_f32_16x16x32_f16 v[2:5], v[184:187], v[224:227], v[2:5]
	v_mfma_f32_16x16x32_f16 v[62:65], v[166:169], v[204:207], v[62:65]
	v_mfma_f32_16x16x32_f16 v[54:57], v[188:191], v[204:207], v[54:57]
	v_mfma_f32_16x16x32_f16 v[46:49], v[166:169], v[212:215], v[46:49]
	v_mfma_f32_16x16x32_f16 v[38:41], v[188:191], v[212:215], v[38:41]
	v_mfma_f32_16x16x32_f16 v[30:33], v[166:169], v[220:223], v[30:33]
	v_mfma_f32_16x16x32_f16 v[22:25], v[188:191], v[220:223], v[22:25]
	v_mfma_f32_16x16x32_f16 v[14:17], v[166:169], v[228:231], v[14:17]
	v_mfma_f32_16x16x32_f16 v[2:5], v[188:191], v[228:231], v[2:5]
	s_barrier
	s_setprio 0
	s_add_u32 s52, s52, 0x100
	s_addc_u32 s53, s53, 0
	s_add_u32 s80, s80, 0x100
	s_addc_u32 s81, s81, 0
	s_cmp_ge_u32 s82, s65
	s_mov_b32 s54, s82
	s_cbranch_scc0 .LBB0_310

; #define PG8_STAGE(bufoff, gbase, voff) do { _Pragma("unroll") for (int _i = 0; _i < 2; ++_i) \
;         __builtin_amdgcn_global_load_lds((const unsigned*)((const char*)(gbase) + (voff)[_i]), (PG8_LAS unsigned*)(lds + (bufoff) + ldsw + _i * 8192), 16, 0, 0); } while (0)
; #define PG8_LDA(dst, b, h) do { _Pragma("unroll") for (int m = 0; m < 4; ++m) _Pragma("unroll") for (int k = 0; k < 2; ++k) dst[m][k] = *(const PG8_LAS bf16x8*)(lds + PG8_SA(b, h) + aoff + m * 2048 + k * 1024); } while (0)
; #define PG8_LDB(dst, b, h) do { _Pragma("unroll") for (int n = 0; n < 2; ++n) _Pragma("unroll") for (int k = 0; k < 2; ++k) dst[n][k] = *(const PG8_LAS bf16x8*)(lds + PG8_SB(b, h) + boff + n * 2048 + k * 1024); } while (0)
; #define PG8_WAIT_V(n) asm volatile("s_waitcnt vmcnt(" #n ")" ::: "memory")
; #define PG8_WAIT_L(n) asm volatile("s_waitcnt lgkmcnt(" #n ")" ::: "memory")
; #define PG8_BAR __builtin_amdgcn_s_barrier()
; #define PG8_SCHED __builtin_amdgcn_sched_barrier(0)
; template <class Epi, class Sched, bool ALIGN_EPI = false, bool SP2 = false, bool F16 = false>
; __device__ __forceinline__ void gemm_phase(PG8_LAS unsigned char* lds, const Gemm g, const Sched& S, const Epi& E) {
;     ...
;         for (int t = 0; t < nt; t += 2) {
;             const bool last = (t == nt - 2);
;             const char* a1 = cA + (size_t)(t + 1) * kstep;
;             const char* a2 = last ? nA : cA + (size_t)(t + 2) * kstep; const char* b2 = last ? nB : cB + (size_t)(t + 2) * kstep;
;             const char* a3 = a2 + kstep; const char* b3 = b2 + kstep;
;             if (last && has_next) S.a_ready(nxt);
;             if constexpr (SP2) {
;             PG8_LDB(B0, 0, 0); PG8_LDB(B1, 0, 1); PG8_SCHED; PG8_LDA(At, 0, 0); PG8_STAGE(PG8_SA(1, 1), a1 + hstepA, voffA);
;             PG8_WAIT_V(8); PG8_WAIT_L(0); PG8_BAR; PG8_MMA(0, 0, At, B0); PG8_MMA(0, 1, At, B1); PG8_BAR; PG8_SCHED;
;             PG8_LDA(At, 0, 1); PG8_STAGE(PG8_SB(0, 0), b2, voffB); PG8_STAGE(PG8_SB(0, 1), b2 + hstepB, voffB); PG8_STAGE(PG8_SA(0, 0), a2, voffA);
;             PG8_WAIT_V(8); PG8_WAIT_L(0); PG8_BAR; PG8_MMA(1, 0, At, B0); PG8_MMA(1, 1, At, B1); PG8_BAR; PG8_SCHED;
.LBB0_345:
	s_add_i32 s81, s54, 2
	s_add_u32 s82, s52, 0x80
	s_addc_u32 s55, s53, 0
	s_add_i32 s94, 0, 0x10000
	s_cmp_eq_u32 s74, s54
	s_cselect_b32 s55, s41, s55
	s_cselect_b32 s54, s40, s82
	s_cselect_b32 s83, s47, s80
	s_cselect_b32 s82, s46, s79
	s_add_i32 s95, 0, 0x14000
	v_add_u32_e32 v152, s94, v158
	v_add_u32_e32 v156, s95, v158
	ds_read_b128 v[130:133], v152
	ds_read_b128 v[134:137], v152 offset:1024
	ds_read_b128 v[148:151], v152 offset:2048
	ds_read_b128 v[152:155], v152 offset:3072
	ds_read_b128 v[162:165], v156
	ds_read_b128 v[166:169], v156 offset:1024
	ds_read_b128 v[170:173], v156 offset:2048
	ds_read_b128 v[182:185], v156 offset:3072
	v_lshl_add_u64 v[156:157], s[52:53], 0, v[144:145]
	s_add_i32 m0, s3, 0xc000
	ds_read_b128 v[186:189], v160
	ds_read_b128 v[190:193], v160 offset:1024
	ds_read_b128 v[194:197], v160 offset:2048
	ds_read_b128 v[204:207], v160 offset:3072
	ds_read_b128 v[208:211], v160 offset:4096
	ds_read_b128 v[212:215], v160 offset:5120
	ds_read_b128 v[216:219], v160 offset:6144
	ds_read_b128 v[220:223], v160 offset:7168
	global_load_lds_dwordx4 v[156:157], off
	v_lshl_add_u64 v[156:157], s[52:53], 0, v[146:147]
	s_add_i32 m0, s3, 0xe000
	s_nop 0
	global_load_lds_dwordx4 v[156:157], off
	s_waitcnt vmcnt(8)
	s_waitcnt lgkmcnt(0)
	s_setprio 1
	s_barrier
	v_mfma_f32_16x16x32_bf16 v[122:125], v[130:133], v[186:189], v[122:125]
	v_mfma_f32_16x16x32_bf16 v[126:129], v[148:151], v[186:189], v[126:129]
	v_mfma_f32_16x16x32_bf16 v[110:113], v[130:133], v[194:197], v[110:113]
	v_mfma_f32_16x16x32_bf16 v[106:109], v[148:151], v[194:197], v[106:109]
	v_mfma_f32_16x16x32_bf16 v[94:97], v[130:133], v[208:211], v[94:97]
	v_mfma_f32_16x16x32_bf16 v[90:93], v[148:151], v[208:211], v[90:93]
	v_mfma_f32_16x16x32_bf16 v[78:81], v[130:133], v[216:219], v[78:81]
	v_mfma_f32_16x16x32_bf16 v[74:77], v[148:151], v[216:219], v[74:77]
	v_mfma_f32_16x16x32_bf16 v[122:125], v[134:137], v[190:193], v[122:125]
	v_mfma_f32_16x16x32_bf16 v[126:129], v[152:155], v[190:193], v[126:129]
	v_mfma_f32_16x16x32_bf16 v[110:113], v[134:137], v[204:207], v[110:113]
	v_mfma_f32_16x16x32_bf16 v[106:109], v[152:155], v[204:207], v[106:109]
	v_mfma_f32_16x16x32_bf16 v[94:97], v[134:137], v[212:215], v[94:97]
	v_mfma_f32_16x16x32_bf16 v[90:93], v[152:155], v[212:215], v[90:93]
	v_mfma_f32_16x16x32_bf16 v[78:81], v[134:137], v[220:223], v[78:81]
	v_mfma_f32_16x16x32_bf16 v[74:77], v[152:155], v[220:223], v[74:77]
	v_mfma_f32_16x16x32_bf16 v[118:121], v[162:165], v[186:189], v[118:121]
	v_mfma_f32_16x16x32_bf16 v[114:117], v[170:173], v[186:189], v[114:117]
	v_mfma_f32_16x16x32_bf16 v[102:105], v[162:165], v[194:197], v[102:105]
	v_mfma_f32_16x16x32_bf16 v[98:101], v[170:173], v[194:197], v[98:101]
	v_mfma_f32_16x16x32_bf16 v[86:89], v[162:165], v[208:211], v[86:89]
	v_mfma_f32_16x16x32_bf16 v[82:85], v[170:173], v[208:211], v[82:85]
	v_mfma_f32_16x16x32_bf16 v[70:73], v[162:165], v[216:219], v[70:73]
	v_mfma_f32_16x16x32_bf16 v[66:69], v[170:173], v[216:219], v[66:69]
	v_mfma_f32_16x16x32_bf16 v[118:121], v[166:169], v[190:193], v[118:121]
	v_mfma_f32_16x16x32_bf16 v[114:117], v[182:185], v[190:193], v[114:117]
	v_mfma_f32_16x16x32_bf16 v[102:105], v[166:169], v[204:207], v[102:105]
	v_mfma_f32_16x16x32_bf16 v[98:101], v[182:185], v[204:207], v[98:101]
	v_mfma_f32_16x16x32_bf16 v[86:89], v[166:169], v[212:215], v[86:89]
	v_mfma_f32_16x16x32_bf16 v[82:85], v[182:185], v[212:215], v[82:85]
	v_mfma_f32_16x16x32_bf16 v[70:73], v[166:169], v[220:223], v[70:73]
	v_mfma_f32_16x16x32_bf16 v[66:69], v[182:185], v[220:223], v[66:69]
	s_barrier
	s_setprio 0
	s_add_i32 s94, s94, s2
	v_lshl_add_u64 v[156:157], s[82:83], 0, v[174:175]
	s_mov_b32 m0, s94
	ds_read_b128 v[186:189], v160 offset:16384
	ds_read_b128 v[190:193], v160 offset:17408
	ds_read_b128 v[194:197], v160 offset:18432
	ds_read_b128 v[204:207], v160 offset:19456
	ds_read_b128 v[208:211], v160 offset:20480
	ds_read_b128 v[212:215], v160 offset:21504
	ds_read_b128 v[216:219], v160 offset:22528
	ds_read_b128 v[220:223], v160 offset:23552
	global_load_lds_dwordx4 v[156:157], off
	s_add_i32 m0, s94, 0x2000
	v_lshl_add_u64 v[176:177], s[82:83], 0, v[142:143]
	s_add_u32 s82, s82, s48
	s_addc_u32 s83, s83, 0
	s_add_i32 s94, s95, s2
	global_load_lds_dwordx4 v[176:177], off
	v_lshl_add_u64 v[224:225], s[82:83], 0, v[174:175]
	s_mov_b32 m0, s94
	v_lshl_add_u64 v[226:227], s[82:83], 0, v[142:143]
	global_load_lds_dwordx4 v[224:225], off
	s_add_i32 m0, s94, 0x2000
	v_lshl_add_u64 v[228:229], s[54:55], 0, v[138:139]
	global_load_lds_dwordx4 v[226:227], off
	s_mov_b32 m0, s3
	v_lshl_add_u64 v[230:231], s[54:55], 0, v[140:141]
	global_load_lds_dwordx4 v[228:229], off
	s_mov_b32 m0, s12
	s_nop 0
	global_load_lds_dwordx4 v[230:231], off
	s_waitcnt vmcnt(8)
	s_waitcnt lgkmcnt(0)
	s_setprio 1
	s_barrier
; #define PG8_STAGE(bufoff, gbase, voff) do { _Pragma("unroll") for (int _i = 0; _i < 2; ++_i) \
;         __builtin_amdgcn_global_load_lds((const unsigned*)((const char*)(gbase) + (voff)[_i]), (PG8_LAS unsigned*)(lds + (bufoff) + ldsw + _i * 8192), 16, 0, 0); } while (0)
; #define PG8_LDA(dst, b, h) do { _Pragma("unroll") for (int m = 0; m < 4; ++m) _Pragma("unroll") for (int k = 0; k < 2; ++k) dst[m][k] = *(const PG8_LAS bf16x8*)(lds + PG8_SA(b, h) + aoff + m * 2048 + k * 1024); } while (0)
; #define PG8_LDB(dst, b, h) do { _Pragma("unroll") for (int n = 0; n < 2; ++n) _Pragma("unroll") for (int k = 0; k < 2; ++k) dst[n][k] = *(const PG8_LAS bf16x8*)(lds + PG8_SB(b, h) + boff + n * 2048 + k * 1024); } while (0)
; #define PG8_WAIT_V(n) asm volatile("s_waitcnt vmcnt(" #n ")" ::: "memory")
; #define PG8_WAIT_L(n) asm volatile("s_waitcnt lgkmcnt(" #n ")" ::: "memory")
; #define PG8_BAR __builtin_amdgcn_s_barrier()
; #define PG8_SCHED __builtin_amdgcn_sched_barrier(0)
; template <class Epi, class Sched, bool ALIGN_EPI = false, bool SP2 = false, bool F16 = false>
; __device__ __forceinline__ void gemm_phase(PG8_LAS unsigned char* lds, const Gemm g, const Sched& S, const Epi& E) {
;     ...
;             PG8_WAIT_V(8); PG8_WAIT_L(0); PG8_BAR; PG8_MMA(1, 0, At, B0); PG8_MMA(1, 1, At, B1); PG8_BAR; PG8_SCHED;
;             PG8_LDB(B0, 1, 0); PG8_LDB(B1, 1, 1); PG8_SCHED; PG8_LDA(At, 1, 0); PG8_STAGE(PG8_SA(0, 1), a2 + hstepA, voffA);
;             PG8_WAIT_V(8); PG8_WAIT_L(0); PG8_BAR; PG8_MMA(0, 0, At, B0); PG8_MMA(0, 1, At, B1); PG8_BAR; PG8_SCHED;
	v_mfma_f32_16x16x32_bf16 v[62:65], v[130:133], v[186:189], v[62:65]
	v_mfma_f32_16x16x32_bf16 v[58:61], v[148:151], v[186:189], v[58:61]
	v_mfma_f32_16x16x32_bf16 v[46:49], v[130:133], v[194:197], v[46:49]
	v_mfma_f32_16x16x32_bf16 v[42:45], v[148:151], v[194:197], v[42:45]
	v_mfma_f32_16x16x32_bf16 v[30:33], v[130:133], v[208:211], v[30:33]
	v_mfma_f32_16x16x32_bf16 v[26:29], v[148:151], v[208:211], v[26:29]
	v_mfma_f32_16x16x32_bf16 v[14:17], v[130:133], v[216:219], v[14:17]
	v_mfma_f32_16x16x32_bf16 v[10:13], v[148:151], v[216:219], v[10:13]
	v_mfma_f32_16x16x32_bf16 v[62:65], v[134:137], v[190:193], v[62:65]
	v_mfma_f32_16x16x32_bf16 v[58:61], v[152:155], v[190:193], v[58:61]
	v_mfma_f32_16x16x32_bf16 v[46:49], v[134:137], v[204:207], v[46:49]
	v_mfma_f32_16x16x32_bf16 v[42:45], v[152:155], v[204:207], v[42:45]
	v_mfma_f32_16x16x32_bf16 v[30:33], v[134:137], v[212:215], v[30:33]
	v_mfma_f32_16x16x32_bf16 v[26:29], v[152:155], v[212:215], v[26:29]
	v_mfma_f32_16x16x32_bf16 v[14:17], v[134:137], v[220:223], v[14:17]
	v_mfma_f32_16x16x32_bf16 v[10:13], v[152:155], v[220:223], v[10:13]
	v_mfma_f32_16x16x32_bf16 v[54:57], v[162:165], v[186:189], v[54:57]
	v_mfma_f32_16x16x32_bf16 v[50:53], v[170:173], v[186:189], v[50:53]
	v_mfma_f32_16x16x32_bf16 v[38:41], v[162:165], v[194:197], v[38:41]
	v_mfma_f32_16x16x32_bf16 v[34:37], v[170:173], v[194:197], v[34:37]
	v_mfma_f32_16x16x32_bf16 v[22:25], v[162:165], v[208:211], v[22:25]
	v_mfma_f32_16x16x32_bf16 v[18:21], v[170:173], v[208:211], v[18:21]
	v_mfma_f32_16x16x32_bf16 v[6:9], v[162:165], v[216:219], v[6:9]
	v_mfma_f32_16x16x32_bf16 v[2:5], v[170:173], v[216:219], v[2:5]
	v_mfma_f32_16x16x32_bf16 v[54:57], v[166:169], v[190:193], v[54:57]
	v_mfma_f32_16x16x32_bf16 v[50:53], v[182:185], v[190:193], v[50:53]
	v_mfma_f32_16x16x32_bf16 v[38:41], v[166:169], v[204:207], v[38:41]
	v_mfma_f32_16x16x32_bf16 v[34:37], v[182:185], v[204:207], v[34:37]
	v_mfma_f32_16x16x32_bf16 v[22:25], v[166:169], v[212:215], v[22:25]
	v_mfma_f32_16x16x32_bf16 v[18:21], v[182:185], v[212:215], v[18:21]
	v_mfma_f32_16x16x32_bf16 v[6:9], v[166:169], v[220:223], v[6:9]
	v_mfma_f32_16x16x32_bf16 v[2:5], v[182:185], v[220:223], v[2:5]
	s_barrier
	s_setprio 0
	s_add_i32 s82, 0, 0x18000
	s_add_i32 s83, 0, 0x1c000
	v_add_u32_e32 v152, s82, v158
	v_add_u32_e32 v161, s83, v158
	ds_read_b128 v[130:133], v152
	ds_read_b128 v[134:137], v152 offset:1024
	ds_read_b128 v[148:151], v152 offset:2048
	ds_read_b128 v[152:155], v152 offset:3072
	ds_read_b128 v[162:165], v161
	ds_read_b128 v[166:169], v161 offset:1024
	ds_read_b128 v[170:173], v161 offset:2048
	ds_read_b128 v[182:185], v161 offset:3072
	s_add_u32 s54, s54, s8
	s_addc_u32 s55, s55, 0
	s_mov_b32 m0, s13
	v_lshl_add_u64 v[232:233], s[54:55], 0, v[138:139]
	ds_read_b128 v[186:189], v160 offset:32768
	ds_read_b128 v[190:193], v160 offset:33792
	ds_read_b128 v[194:197], v160 offset:34816
	ds_read_b128 v[204:207], v160 offset:35840
	ds_read_b128 v[208:211], v160 offset:36864
	ds_read_b128 v[212:215], v160 offset:37888
	ds_read_b128 v[216:219], v160 offset:38912
	ds_read_b128 v[220:223], v160 offset:39936
	global_load_lds_dwordx4 v[232:233], off
	v_lshl_add_u64 v[232:233], s[54:55], 0, v[140:141]
	s_mov_b32 m0, s22
	s_nop 0
	global_load_lds_dwordx4 v[232:233], off
	s_waitcnt vmcnt(8)
	s_waitcnt lgkmcnt(0)
	s_setprio 1
	s_barrier
	v_mfma_f32_16x16x32_bf16 v[122:125], v[130:133], v[186:189], v[122:125]
	v_mfma_f32_16x16x32_bf16 v[126:129], v[148:151], v[186:189], v[126:129]
	v_mfma_f32_16x16x32_bf16 v[110:113], v[130:133], v[194:197], v[110:113]
	v_mfma_f32_16x16x32_bf16 v[106:109], v[148:151], v[194:197], v[106:109]
	v_mfma_f32_16x16x32_bf16 v[94:97], v[130:133], v[208:211], v[94:97]
	v_mfma_f32_16x16x32_bf16 v[90:93], v[148:151], v[208:211], v[90:93]
	v_mfma_f32_16x16x32_bf16 v[78:81], v[130:133], v[216:219], v[78:81]
	v_mfma_f32_16x16x32_bf16 v[74:77], v[148:151], v[216:219], v[74:77]
	v_mfma_f32_16x16x32_bf16 v[122:125], v[134:137], v[190:193], v[122:125]
	v_mfma_f32_16x16x32_bf16 v[126:129], v[152:155], v[190:193], v[126:129]
	v_mfma_f32_16x16x32_bf16 v[110:113], v[134:137], v[204:207], v[110:113]
	v_mfma_f32_16x16x32_bf16 v[106:109], v[152:155], v[204:207], v[106:109]
	v_mfma_f32_16x16x32_bf16 v[94:97], v[134:137], v[212:215], v[94:97]
	v_mfma_f32_16x16x32_bf16 v[90:93], v[152:155], v[212:215], v[90:93]
	v_mfma_f32_16x16x32_bf16 v[78:81], v[134:137], v[220:223], v[78:81]
	v_mfma_f32_16x16x32_bf16 v[74:77], v[152:155], v[220:223], v[74:77]
	v_mfma_f32_16x16x32_bf16 v[118:121], v[162:165], v[186:189], v[118:121]
	v_mfma_f32_16x16x32_bf16 v[114:117], v[170:173], v[186:189], v[114:117]
	v_mfma_f32_16x16x32_bf16 v[102:105], v[162:165], v[194:197], v[102:105]
	v_mfma_f32_16x16x32_bf16 v[98:101], v[170:173], v[194:197], v[98:101]
	v_mfma_f32_16x16x32_bf16 v[86:89], v[162:165], v[208:211], v[86:89]
	v_mfma_f32_16x16x32_bf16 v[82:85], v[170:173], v[208:211], v[82:85]
	v_mfma_f32_16x16x32_bf16 v[70:73], v[162:165], v[216:219], v[70:73]
	v_mfma_f32_16x16x32_bf16 v[66:69], v[170:173], v[216:219], v[66:69]
	v_mfma_f32_16x16x32_bf16 v[118:121], v[166:169], v[190:193], v[118:121]
	v_mfma_f32_16x16x32_bf16 v[114:117], v[182:185], v[190:193], v[114:117]
	v_mfma_f32_16x16x32_bf16 v[102:105], v[166:169], v[204:207], v[102:105]
	v_mfma_f32_16x16x32_bf16 v[98:101], v[182:185], v[204:207], v[98:101]
	v_mfma_f32_16x16x32_bf16 v[86:89], v[166:169], v[212:215], v[86:89]
	v_mfma_f32_16x16x32_bf16 v[82:85], v[182:185], v[212:215], v[82:85]
	v_mfma_f32_16x16x32_bf16 v[70:73], v[166:169], v[220:223], v[70:73]
	v_mfma_f32_16x16x32_bf16 v[66:69], v[182:185], v[220:223], v[66:69]
	s_barrier
; #define PG8_STAGE(bufoff, gbase, voff) do { _Pragma("unroll") for (int _i = 0; _i < 2; ++_i) \
;         __builtin_amdgcn_global_load_lds((const unsigned*)((const char*)(gbase) + (voff)[_i]), (PG8_LAS unsigned*)(lds + (bufoff) + ldsw + _i * 8192), 16, 0, 0); } while (0)
; #define PG8_LDA(dst, b, h) do { _Pragma("unroll") for (int m = 0; m < 4; ++m) _Pragma("unroll") for (int k = 0; k < 2; ++k) dst[m][k] = *(const PG8_LAS bf16x8*)(lds + PG8_SA(b, h) + aoff + m * 2048 + k * 1024); } while (0)
; #define PG8_WAIT_V(n) asm volatile("s_waitcnt vmcnt(" #n ")" ::: "memory")
; #define PG8_WAIT_L(n) asm volatile("s_waitcnt lgkmcnt(" #n ")" ::: "memory")
; #define PG8_BAR __builtin_amdgcn_s_barrier()
; #define PG8_SCHED __builtin_amdgcn_sched_barrier(0)
; template <class Epi, class Sched, bool ALIGN_EPI = false, bool SP2 = false, bool F16 = false>
; __device__ __forceinline__ void gemm_phase(PG8_LAS unsigned char* lds, const Gemm g, const Sched& S, const Epi& E) {
;     ...
;             PG8_LDA(At, 1, 1); PG8_STAGE(PG8_SB(1, 0), b3, voffB); PG8_STAGE(PG8_SB(1, 1), b3 + hstepB, voffB); PG8_STAGE(PG8_SA(1, 0), a3, voffA);
;             PG8_WAIT_V(8); PG8_WAIT_L(0); PG8_BAR; PG8_MMA(1, 0, At, B0); PG8_MMA(1, 1, At, B1); PG8_BAR; PG8_SCHED;
	s_setprio 0
	s_add_i32 s54, s82, s2
	v_lshl_add_u64 v[156:157], v[156:157], 0, s[92:93]
	s_mov_b32 m0, s54
	ds_read_b128 v[186:189], v160 offset:49152
	ds_read_b128 v[190:193], v160 offset:50176
	ds_read_b128 v[194:197], v160 offset:51200
	ds_read_b128 v[204:207], v160 offset:52224
	ds_read_b128 v[208:211], v160 offset:53248
	ds_read_b128 v[212:215], v160 offset:54272
	ds_read_b128 v[216:219], v160 offset:55296
	ds_read_b128 v[220:223], v160 offset:56320
	global_load_lds_dwordx4 v[156:157], off
	v_lshl_add_u64 v[156:157], v[176:177], 0, s[92:93]
	s_add_i32 m0, s54, 0x2000
	s_add_i32 s54, s83, s2
	global_load_lds_dwordx4 v[156:157], off
	v_lshl_add_u64 v[156:157], v[224:225], 0, s[92:93]
	s_mov_b32 m0, s54
	s_nop 0
	global_load_lds_dwordx4 v[156:157], off
	v_lshl_add_u64 v[156:157], v[226:227], 0, s[92:93]
	s_add_i32 m0, s54, 0x2000
	s_nop 0
	global_load_lds_dwordx4 v[156:157], off
	v_lshl_add_u64 v[156:157], v[228:229], 0, s[92:93]
	s_mov_b32 m0, s33
	s_nop 0
	global_load_lds_dwordx4 v[156:157], off
	v_lshl_add_u64 v[156:157], v[230:231], 0, s[92:93]
	s_mov_b32 m0, s35
	s_nop 0
	global_load_lds_dwordx4 v[156:157], off
	s_waitcnt vmcnt(8)
	s_waitcnt lgkmcnt(0)
	s_setprio 1
	s_barrier
	v_mfma_f32_16x16x32_bf16 v[62:65], v[130:133], v[186:189], v[62:65]
	v_mfma_f32_16x16x32_bf16 v[58:61], v[148:151], v[186:189], v[58:61]
	v_mfma_f32_16x16x32_bf16 v[46:49], v[130:133], v[194:197], v[46:49]
	v_mfma_f32_16x16x32_bf16 v[42:45], v[148:151], v[194:197], v[42:45]
	v_mfma_f32_16x16x32_bf16 v[30:33], v[130:133], v[208:211], v[30:33]
	v_mfma_f32_16x16x32_bf16 v[26:29], v[148:151], v[208:211], v[26:29]
	v_mfma_f32_16x16x32_bf16 v[14:17], v[130:133], v[216:219], v[14:17]
	v_mfma_f32_16x16x32_bf16 v[10:13], v[148:151], v[216:219], v[10:13]
	v_mfma_f32_16x16x32_bf16 v[62:65], v[134:137], v[190:193], v[62:65]
	v_mfma_f32_16x16x32_bf16 v[58:61], v[152:155], v[190:193], v[58:61]
	v_mfma_f32_16x16x32_bf16 v[46:49], v[134:137], v[204:207], v[46:49]
	v_mfma_f32_16x16x32_bf16 v[42:45], v[152:155], v[204:207], v[42:45]
	v_mfma_f32_16x16x32_bf16 v[30:33], v[134:137], v[212:215], v[30:33]
	v_mfma_f32_16x16x32_bf16 v[26:29], v[152:155], v[212:215], v[26:29]
	v_mfma_f32_16x16x32_bf16 v[14:17], v[134:137], v[220:223], v[14:17]
	v_mfma_f32_16x16x32_bf16 v[10:13], v[152:155], v[220:223], v[10:13]
	v_mfma_f32_16x16x32_bf16 v[54:57], v[162:165], v[186:189], v[54:57]
	v_mfma_f32_16x16x32_bf16 v[50:53], v[170:173], v[186:189], v[50:53]
	v_mfma_f32_16x16x32_bf16 v[38:41], v[162:165], v[194:197], v[38:41]
	v_mfma_f32_16x16x32_bf16 v[34:37], v[170:173], v[194:197], v[34:37]
	v_mfma_f32_16x16x32_bf16 v[22:25], v[162:165], v[208:211], v[22:25]
	v_mfma_f32_16x16x32_bf16 v[18:21], v[170:173], v[208:211], v[18:21]
	v_mfma_f32_16x16x32_bf16 v[6:9], v[162:165], v[216:219], v[6:9]
	v_mfma_f32_16x16x32_bf16 v[2:5], v[170:173], v[216:219], v[2:5]
	v_mfma_f32_16x16x32_bf16 v[54:57], v[166:169], v[190:193], v[54:57]
	v_mfma_f32_16x16x32_bf16 v[50:53], v[182:185], v[190:193], v[50:53]
	v_mfma_f32_16x16x32_bf16 v[38:41], v[166:169], v[204:207], v[38:41]
	v_mfma_f32_16x16x32_bf16 v[34:37], v[182:185], v[204:207], v[34:37]
	v_mfma_f32_16x16x32_bf16 v[22:25], v[166:169], v[212:215], v[22:25]
	v_mfma_f32_16x16x32_bf16 v[18:21], v[182:185], v[212:215], v[18:21]
	v_mfma_f32_16x16x32_bf16 v[6:9], v[166:169], v[220:223], v[6:9]
	v_mfma_f32_16x16x32_bf16 v[2:5], v[182:185], v[220:223], v[2:5]
	s_barrier
	s_setprio 0
	s_add_u32 s52, s52, 0x100
	s_addc_u32 s53, s53, 0
	s_add_u32 s79, s79, 0x100
	s_addc_u32 s80, s80, 0
	s_cmp_ge_u32 s81, s65
	s_mov_b32 s54, s81
	s_cbranch_scc0 .LBB0_345

; #define PG8_STAGE(bufoff, gbase, voff) do { _Pragma("unroll") for (int _i = 0; _i < 2; ++_i) \
;         __builtin_amdgcn_global_load_lds((const unsigned*)((const char*)(gbase) + (voff)[_i]), (PG8_LAS unsigned*)(lds + (bufoff) + ldsw + _i * 8192), 16, 0, 0); } while (0)
; #define PG8_LDA(dst, b, h) do { _Pragma("unroll") for (int m = 0; m < 4; ++m) _Pragma("unroll") for (int k = 0; k < 2; ++k) dst[m][k] = *(const PG8_LAS bf16x8*)(lds + PG8_SA(b, h) + aoff + m * 2048 + k * 1024); } while (0)
; #define PG8_LDB(dst, b, h) do { _Pragma("unroll") for (int n = 0; n < 2; ++n) _Pragma("unroll") for (int k = 0; k < 2; ++k) dst[n][k] = *(const PG8_LAS bf16x8*)(lds + PG8_SB(b, h) + boff + n * 2048 + k * 1024); } while (0)
; #define PG8_WAIT_V(n) asm volatile("s_waitcnt vmcnt(" #n ")" ::: "memory")
; #define PG8_WAIT_L(n) asm volatile("s_waitcnt lgkmcnt(" #n ")" ::: "memory")
; #define PG8_BAR __builtin_amdgcn_s_barrier()
; #define PG8_SCHED __builtin_amdgcn_sched_barrier(0)
; template <class Epi, class Sched, bool ALIGN_EPI = false, bool SP2 = false, bool F16 = false>
; __device__ __forceinline__ void gemm_phase(PG8_LAS unsigned char* lds, const Gemm g, const Sched& S, const Epi& E) {
;     ...
;         for (int t = 0; t < nt; t += 2) {
;             const bool last = (t == nt - 2);
;             const char* a1 = cA + (size_t)(t + 1) * kstep;
;             const char* a2 = last ? nA : cA + (size_t)(t + 2) * kstep; const char* b2 = last ? nB : cB + (size_t)(t + 2) * kstep;
;             const char* a3 = a2 + kstep; const char* b3 = b2 + kstep;
;             if (last && has_next) S.a_ready(nxt);
;             if constexpr (SP2) {
;             PG8_LDB(B0, 0, 0); PG8_LDB(B1, 0, 1); PG8_SCHED; PG8_LDA(At, 0, 0); PG8_STAGE(PG8_SA(1, 1), a1 + hstepA, voffA);
;             PG8_WAIT_V(8); PG8_WAIT_L(0); PG8_BAR; PG8_MMA(0, 0, At, B0); PG8_MMA(0, 1, At, B1); PG8_BAR; PG8_SCHED;
;             PG8_LDA(At, 0, 1); PG8_STAGE(PG8_SB(0, 0), b2, voffB); PG8_STAGE(PG8_SB(0, 1), b2 + hstepB, voffB); PG8_STAGE(PG8_SA(0, 0), a2, voffA);
;             PG8_WAIT_V(8); PG8_WAIT_L(0); PG8_BAR; PG8_MMA(1, 0, At, B0); PG8_MMA(1, 1, At, B1); PG8_BAR; PG8_SCHED;
.LBB0_398:
	s_add_i32 s78, s72, 2
	s_add_u32 s79, s46, 0x80
	s_addc_u32 s73, s47, 0
	s_add_i32 vcc_lo, 0, 0x10000
	s_cmp_eq_u32 s74, s72
	s_cselect_b32 s73, s55, s73
	s_cselect_b32 s72, s54, s79
	s_cselect_b32 s95, s53, s24
	s_cselect_b32 s94, s52, s13
	s_add_i32 s79, 0, 0x14000
	v_add_u32_e32 v142, vcc_lo, v163
	v_add_u32_e32 v172, s79, v163
	ds_read_b128 v[130:133], v142
	ds_read_b128 v[134:137], v142 offset:1024
	ds_read_b128 v[138:141], v142 offset:2048
	ds_read_b128 v[142:145], v142 offset:3072
	ds_read_b128 v[146:149], v172
	ds_read_b128 v[150:153], v172 offset:1024
	ds_read_b128 v[182:185], v172 offset:2048
	ds_read_b128 v[186:189], v172 offset:3072
	v_lshl_add_u64 v[172:173], s[46:47], 0, v[168:169]
	s_add_i32 m0, s36, 0xc000
	ds_read_b128 v[190:193], v204
	ds_read_b128 v[194:197], v204 offset:1024
	ds_read_b128 v[206:209], v204 offset:2048
	ds_read_b128 v[210:213], v204 offset:3072
	ds_read_b128 v[214:217], v204 offset:4096
	ds_read_b128 v[218:221], v204 offset:5120
	ds_read_b128 v[222:225], v204 offset:6144
	ds_read_b128 v[226:229], v204 offset:7168
	global_load_lds_dwordx4 v[172:173], off
	v_lshl_add_u64 v[172:173], s[46:47], 0, v[170:171]
	s_add_i32 m0, s36, 0xe000
	s_nop 0
	global_load_lds_dwordx4 v[172:173], off
	s_waitcnt vmcnt(8)
	s_waitcnt lgkmcnt(0)
	s_setprio 1
	s_barrier
	v_mfma_f32_16x16x32_bf16 v[122:125], v[130:133], v[190:193], v[122:125]
	v_mfma_f32_16x16x32_bf16 v[126:129], v[138:141], v[190:193], v[126:129]
	v_mfma_f32_16x16x32_bf16 v[110:113], v[130:133], v[206:209], v[110:113]
	v_mfma_f32_16x16x32_bf16 v[106:109], v[138:141], v[206:209], v[106:109]
	v_mfma_f32_16x16x32_bf16 v[94:97], v[130:133], v[214:217], v[94:97]
	v_mfma_f32_16x16x32_bf16 v[90:93], v[138:141], v[214:217], v[90:93]
	v_mfma_f32_16x16x32_bf16 v[78:81], v[130:133], v[222:225], v[78:81]
	v_mfma_f32_16x16x32_bf16 v[74:77], v[138:141], v[222:225], v[74:77]
	v_mfma_f32_16x16x32_bf16 v[122:125], v[134:137], v[194:197], v[122:125]
	v_mfma_f32_16x16x32_bf16 v[126:129], v[142:145], v[194:197], v[126:129]
	v_mfma_f32_16x16x32_bf16 v[110:113], v[134:137], v[210:213], v[110:113]
	v_mfma_f32_16x16x32_bf16 v[106:109], v[142:145], v[210:213], v[106:109]
	v_mfma_f32_16x16x32_bf16 v[94:97], v[134:137], v[218:221], v[94:97]
	v_mfma_f32_16x16x32_bf16 v[90:93], v[142:145], v[218:221], v[90:93]
	v_mfma_f32_16x16x32_bf16 v[78:81], v[134:137], v[226:229], v[78:81]
	v_mfma_f32_16x16x32_bf16 v[74:77], v[142:145], v[226:229], v[74:77]
	v_mfma_f32_16x16x32_bf16 v[118:121], v[146:149], v[190:193], v[118:121]
	v_mfma_f32_16x16x32_bf16 v[114:117], v[182:185], v[190:193], v[114:117]
	v_mfma_f32_16x16x32_bf16 v[102:105], v[146:149], v[206:209], v[102:105]
	v_mfma_f32_16x16x32_bf16 v[98:101], v[182:185], v[206:209], v[98:101]
	v_mfma_f32_16x16x32_bf16 v[86:89], v[146:149], v[214:217], v[86:89]
	v_mfma_f32_16x16x32_bf16 v[82:85], v[182:185], v[214:217], v[82:85]
	v_mfma_f32_16x16x32_bf16 v[70:73], v[146:149], v[222:225], v[70:73]
	v_mfma_f32_16x16x32_bf16 v[66:69], v[182:185], v[222:225], v[66:69]
	v_mfma_f32_16x16x32_bf16 v[118:121], v[150:153], v[194:197], v[118:121]
	v_mfma_f32_16x16x32_bf16 v[114:117], v[186:189], v[194:197], v[114:117]
	v_mfma_f32_16x16x32_bf16 v[102:105], v[150:153], v[210:213], v[102:105]
	v_mfma_f32_16x16x32_bf16 v[98:101], v[186:189], v[210:213], v[98:101]
	v_mfma_f32_16x16x32_bf16 v[86:89], v[150:153], v[218:221], v[86:89]
	v_mfma_f32_16x16x32_bf16 v[82:85], v[186:189], v[218:221], v[82:85]
	v_mfma_f32_16x16x32_bf16 v[70:73], v[150:153], v[226:229], v[70:73]
	v_mfma_f32_16x16x32_bf16 v[66:69], v[186:189], v[226:229], v[66:69]
	s_barrier
	s_setprio 0
	s_add_i32 vcc_lo, vcc_lo, s75
	v_lshl_add_u64 v[172:173], s[94:95], 0, v[156:157]
	s_mov_b32 m0, vcc_lo
	ds_read_b128 v[190:193], v204 offset:16384
	ds_read_b128 v[194:197], v204 offset:17408
	ds_read_b128 v[206:209], v204 offset:18432
	ds_read_b128 v[210:213], v204 offset:19456
	ds_read_b128 v[214:217], v204 offset:20480
	ds_read_b128 v[218:221], v204 offset:21504
	ds_read_b128 v[222:225], v204 offset:22528
	ds_read_b128 v[226:229], v204 offset:23552
	global_load_lds_dwordx4 v[172:173], off
	s_add_i32 m0, vcc_lo, 0x2000
	v_lshl_add_u64 v[176:177], s[94:95], 0, v[160:161]
	s_add_u32 s94, s94, s48
	s_addc_u32 s95, s95, 0
	s_add_i32 s79, s79, s75
	global_load_lds_dwordx4 v[176:177], off
	v_lshl_add_u64 v[230:231], s[94:95], 0, v[156:157]
	s_mov_b32 m0, s79
	v_lshl_add_u64 v[232:233], s[94:95], 0, v[160:161]
	global_load_lds_dwordx4 v[230:231], off
	s_add_i32 m0, s79, 0x2000
	v_lshl_add_u64 v[234:235], s[72:73], 0, v[154:155]
	global_load_lds_dwordx4 v[232:233], off
	s_mov_b32 m0, s36
	v_lshl_add_u64 v[236:237], s[72:73], 0, v[158:159]
	global_load_lds_dwordx4 v[234:235], off
	s_mov_b32 m0, s37
	s_nop 0
	global_load_lds_dwordx4 v[236:237], off
	s_waitcnt vmcnt(8)
	s_waitcnt lgkmcnt(0)
	s_setprio 1
	s_barrier
; #define PG8_STAGE(bufoff, gbase, voff) do { _Pragma("unroll") for (int _i = 0; _i < 2; ++_i) \
;         __builtin_amdgcn_global_load_lds((const unsigned*)((const char*)(gbase) + (voff)[_i]), (PG8_LAS unsigned*)(lds + (bufoff) + ldsw + _i * 8192), 16, 0, 0); } while (0)
; #define PG8_LDA(dst, b, h) do { _Pragma("unroll") for (int m = 0; m < 4; ++m) _Pragma("unroll") for (int k = 0; k < 2; ++k) dst[m][k] = *(const PG8_LAS bf16x8*)(lds + PG8_SA(b, h) + aoff + m * 2048 + k * 1024); } while (0)
; #define PG8_LDB(dst, b, h) do { _Pragma("unroll") for (int n = 0; n < 2; ++n) _Pragma("unroll") for (int k = 0; k < 2; ++k) dst[n][k] = *(const PG8_LAS bf16x8*)(lds + PG8_SB(b, h) + boff + n * 2048 + k * 1024); } while (0)
; #define PG8_WAIT_V(n) asm volatile("s_waitcnt vmcnt(" #n ")" ::: "memory")
; #define PG8_WAIT_L(n) asm volatile("s_waitcnt lgkmcnt(" #n ")" ::: "memory")
; #define PG8_BAR __builtin_amdgcn_s_barrier()
; #define PG8_SCHED __builtin_amdgcn_sched_barrier(0)
; template <class Epi, class Sched, bool ALIGN_EPI = false, bool SP2 = false, bool F16 = false>
; __device__ __forceinline__ void gemm_phase(PG8_LAS unsigned char* lds, const Gemm g, const Sched& S, const Epi& E) {
;     ...
;             PG8_WAIT_V(8); PG8_WAIT_L(0); PG8_BAR; PG8_MMA(1, 0, At, B0); PG8_MMA(1, 1, At, B1); PG8_BAR; PG8_SCHED;
;             PG8_LDB(B0, 1, 0); PG8_LDB(B1, 1, 1); PG8_SCHED; PG8_LDA(At, 1, 0); PG8_STAGE(PG8_SA(0, 1), a2 + hstepA, voffA);
;             PG8_WAIT_V(8); PG8_WAIT_L(0); PG8_BAR; PG8_MMA(0, 0, At, B0); PG8_MMA(0, 1, At, B1); PG8_BAR; PG8_SCHED;
	v_mfma_f32_16x16x32_bf16 v[62:65], v[130:133], v[190:193], v[62:65]
	v_mfma_f32_16x16x32_bf16 v[58:61], v[138:141], v[190:193], v[58:61]
	v_mfma_f32_16x16x32_bf16 v[46:49], v[130:133], v[206:209], v[46:49]
	v_mfma_f32_16x16x32_bf16 v[42:45], v[138:141], v[206:209], v[42:45]
	v_mfma_f32_16x16x32_bf16 v[30:33], v[130:133], v[214:217], v[30:33]
	v_mfma_f32_16x16x32_bf16 v[26:29], v[138:141], v[214:217], v[26:29]
	v_mfma_f32_16x16x32_bf16 v[14:17], v[130:133], v[222:225], v[14:17]
	v_mfma_f32_16x16x32_bf16 v[10:13], v[138:141], v[222:225], v[10:13]
	v_mfma_f32_16x16x32_bf16 v[62:65], v[134:137], v[194:197], v[62:65]
	v_mfma_f32_16x16x32_bf16 v[58:61], v[142:145], v[194:197], v[58:61]
	v_mfma_f32_16x16x32_bf16 v[46:49], v[134:137], v[210:213], v[46:49]
	v_mfma_f32_16x16x32_bf16 v[42:45], v[142:145], v[210:213], v[42:45]
	v_mfma_f32_16x16x32_bf16 v[30:33], v[134:137], v[218:221], v[30:33]
	v_mfma_f32_16x16x32_bf16 v[26:29], v[142:145], v[218:221], v[26:29]
	v_mfma_f32_16x16x32_bf16 v[14:17], v[134:137], v[226:229], v[14:17]
	v_mfma_f32_16x16x32_bf16 v[10:13], v[142:145], v[226:229], v[10:13]
	v_mfma_f32_16x16x32_bf16 v[54:57], v[146:149], v[190:193], v[54:57]
	v_mfma_f32_16x16x32_bf16 v[50:53], v[182:185], v[190:193], v[50:53]
	v_mfma_f32_16x16x32_bf16 v[38:41], v[146:149], v[206:209], v[38:41]
	v_mfma_f32_16x16x32_bf16 v[34:37], v[182:185], v[206:209], v[34:37]
	v_mfma_f32_16x16x32_bf16 v[22:25], v[146:149], v[214:217], v[22:25]
	v_mfma_f32_16x16x32_bf16 v[18:21], v[182:185], v[214:217], v[18:21]
	v_mfma_f32_16x16x32_bf16 v[6:9], v[146:149], v[222:225], v[6:9]
	v_mfma_f32_16x16x32_bf16 v[2:5], v[182:185], v[222:225], v[2:5]
	v_mfma_f32_16x16x32_bf16 v[54:57], v[150:153], v[194:197], v[54:57]
	v_mfma_f32_16x16x32_bf16 v[50:53], v[186:189], v[194:197], v[50:53]
	v_mfma_f32_16x16x32_bf16 v[38:41], v[150:153], v[210:213], v[38:41]
	v_mfma_f32_16x16x32_bf16 v[34:37], v[186:189], v[210:213], v[34:37]
	v_mfma_f32_16x16x32_bf16 v[22:25], v[150:153], v[218:221], v[22:25]
	v_mfma_f32_16x16x32_bf16 v[18:21], v[186:189], v[218:221], v[18:21]
	v_mfma_f32_16x16x32_bf16 v[6:9], v[150:153], v[226:229], v[6:9]
	v_mfma_f32_16x16x32_bf16 v[2:5], v[186:189], v[226:229], v[2:5]
	s_barrier
	s_setprio 0
	s_add_i32 s79, 0, 0x18000
	s_add_i32 s94, 0, 0x1c000
	v_add_u32_e32 v142, s79, v163
	v_add_u32_e32 v174, s94, v163
	ds_read_b128 v[130:133], v142
	ds_read_b128 v[134:137], v142 offset:1024
	ds_read_b128 v[138:141], v142 offset:2048
	ds_read_b128 v[142:145], v142 offset:3072
	ds_read_b128 v[146:149], v174
	ds_read_b128 v[150:153], v174 offset:1024
	ds_read_b128 v[182:185], v174 offset:2048
	ds_read_b128 v[186:189], v174 offset:3072
	s_add_u32 s72, s72, s8
	s_addc_u32 s73, s73, 0
	s_mov_b32 m0, s35
	v_lshl_add_u64 v[238:239], s[72:73], 0, v[154:155]
	ds_read_b128 v[190:193], v204 offset:32768
	ds_read_b128 v[194:197], v204 offset:33792
	ds_read_b128 v[206:209], v204 offset:34816
	ds_read_b128 v[210:213], v204 offset:35840
	ds_read_b128 v[214:217], v204 offset:36864
	ds_read_b128 v[218:221], v204 offset:37888
	ds_read_b128 v[222:225], v204 offset:38912
	ds_read_b128 v[226:229], v204 offset:39936
	global_load_lds_dwordx4 v[238:239], off
	v_lshl_add_u64 v[238:239], s[72:73], 0, v[158:159]
	s_mov_b32 m0, s2
	s_nop 0
	global_load_lds_dwordx4 v[238:239], off
	s_waitcnt vmcnt(8)
	s_waitcnt lgkmcnt(0)
	s_setprio 1
	s_barrier
	v_mfma_f32_16x16x32_bf16 v[122:125], v[130:133], v[190:193], v[122:125]
	v_mfma_f32_16x16x32_bf16 v[126:129], v[138:141], v[190:193], v[126:129]
	v_mfma_f32_16x16x32_bf16 v[110:113], v[130:133], v[206:209], v[110:113]
	v_mfma_f32_16x16x32_bf16 v[106:109], v[138:141], v[206:209], v[106:109]
	v_mfma_f32_16x16x32_bf16 v[94:97], v[130:133], v[214:217], v[94:97]
	v_mfma_f32_16x16x32_bf16 v[90:93], v[138:141], v[214:217], v[90:93]
	v_mfma_f32_16x16x32_bf16 v[78:81], v[130:133], v[222:225], v[78:81]
	v_mfma_f32_16x16x32_bf16 v[74:77], v[138:141], v[222:225], v[74:77]
	v_mfma_f32_16x16x32_bf16 v[122:125], v[134:137], v[194:197], v[122:125]
	v_mfma_f32_16x16x32_bf16 v[126:129], v[142:145], v[194:197], v[126:129]
	v_mfma_f32_16x16x32_bf16 v[110:113], v[134:137], v[210:213], v[110:113]
	v_mfma_f32_16x16x32_bf16 v[106:109], v[142:145], v[210:213], v[106:109]
	v_mfma_f32_16x16x32_bf16 v[94:97], v[134:137], v[218:221], v[94:97]
	v_mfma_f32_16x16x32_bf16 v[90:93], v[142:145], v[218:221], v[90:93]
	v_mfma_f32_16x16x32_bf16 v[78:81], v[134:137], v[226:229], v[78:81]
	v_mfma_f32_16x16x32_bf16 v[74:77], v[142:145], v[226:229], v[74:77]
	v_mfma_f32_16x16x32_bf16 v[118:121], v[146:149], v[190:193], v[118:121]
	v_mfma_f32_16x16x32_bf16 v[114:117], v[182:185], v[190:193], v[114:117]
	v_mfma_f32_16x16x32_bf16 v[102:105], v[146:149], v[206:209], v[102:105]
	v_mfma_f32_16x16x32_bf16 v[98:101], v[182:185], v[206:209], v[98:101]
	v_mfma_f32_16x16x32_bf16 v[86:89], v[146:149], v[214:217], v[86:89]
	v_mfma_f32_16x16x32_bf16 v[82:85], v[182:185], v[214:217], v[82:85]
	v_mfma_f32_16x16x32_bf16 v[70:73], v[146:149], v[222:225], v[70:73]
	v_mfma_f32_16x16x32_bf16 v[66:69], v[182:185], v[222:225], v[66:69]
	v_mfma_f32_16x16x32_bf16 v[118:121], v[150:153], v[194:197], v[118:121]
	v_mfma_f32_16x16x32_bf16 v[114:117], v[186:189], v[194:197], v[114:117]
	v_mfma_f32_16x16x32_bf16 v[102:105], v[150:153], v[210:213], v[102:105]
	v_mfma_f32_16x16x32_bf16 v[98:101], v[186:189], v[210:213], v[98:101]
	v_mfma_f32_16x16x32_bf16 v[86:89], v[150:153], v[218:221], v[86:89]
	v_mfma_f32_16x16x32_bf16 v[82:85], v[186:189], v[218:221], v[82:85]
	v_mfma_f32_16x16x32_bf16 v[70:73], v[150:153], v[226:229], v[70:73]
	v_mfma_f32_16x16x32_bf16 v[66:69], v[186:189], v[226:229], v[66:69]
	s_barrier
; #define PG8_STAGE(bufoff, gbase, voff) do { _Pragma("unroll") for (int _i = 0; _i < 2; ++_i) \
;         __builtin_amdgcn_global_load_lds((const unsigned*)((const char*)(gbase) + (voff)[_i]), (PG8_LAS unsigned*)(lds + (bufoff) + ldsw + _i * 8192), 16, 0, 0); } while (0)
; #define PG8_LDA(dst, b, h) do { _Pragma("unroll") for (int m = 0; m < 4; ++m) _Pragma("unroll") for (int k = 0; k < 2; ++k) dst[m][k] = *(const PG8_LAS bf16x8*)(lds + PG8_SA(b, h) + aoff + m * 2048 + k * 1024); } while (0)
; #define PG8_WAIT_V(n) asm volatile("s_waitcnt vmcnt(" #n ")" ::: "memory")
; #define PG8_WAIT_L(n) asm volatile("s_waitcnt lgkmcnt(" #n ")" ::: "memory")
; #define PG8_BAR __builtin_amdgcn_s_barrier()
; #define PG8_SCHED __builtin_amdgcn_sched_barrier(0)
; template <class Epi, class Sched, bool ALIGN_EPI = false, bool SP2 = false, bool F16 = false>
; __device__ __forceinline__ void gemm_phase(PG8_LAS unsigned char* lds, const Gemm g, const Sched& S, const Epi& E) {
;     ...
;             PG8_LDA(At, 1, 1); PG8_STAGE(PG8_SB(1, 0), b3, voffB); PG8_STAGE(PG8_SB(1, 1), b3 + hstepB, voffB); PG8_STAGE(PG8_SA(1, 0), a3, voffA);
;             PG8_WAIT_V(8); PG8_WAIT_L(0); PG8_BAR; PG8_MMA(1, 0, At, B0); PG8_MMA(1, 1, At, B1); PG8_BAR; PG8_SCHED;
	s_setprio 0
	s_add_i32 s72, s79, s75
	v_lshl_add_u64 v[172:173], v[172:173], 0, s[92:93]
	s_mov_b32 m0, s72
	ds_read_b128 v[190:193], v204 offset:49152
	ds_read_b128 v[194:197], v204 offset:50176
	ds_read_b128 v[206:209], v204 offset:51200
	ds_read_b128 v[210:213], v204 offset:52224
	ds_read_b128 v[214:217], v204 offset:53248
	ds_read_b128 v[218:221], v204 offset:54272
	ds_read_b128 v[222:225], v204 offset:55296
	ds_read_b128 v[226:229], v204 offset:56320
	global_load_lds_dwordx4 v[172:173], off
	v_lshl_add_u64 v[172:173], v[176:177], 0, s[92:93]
	s_add_i32 m0, s72, 0x2000
	s_add_i32 s72, s94, s75
	global_load_lds_dwordx4 v[172:173], off
	v_lshl_add_u64 v[172:173], v[230:231], 0, s[92:93]
	s_mov_b32 m0, s72
	s_nop 0
	global_load_lds_dwordx4 v[172:173], off
	v_lshl_add_u64 v[172:173], v[232:233], 0, s[92:93]
	s_add_i32 m0, s72, 0x2000
	s_nop 0
	global_load_lds_dwordx4 v[172:173], off
	v_lshl_add_u64 v[172:173], v[234:235], 0, s[92:93]
	s_mov_b32 m0, s22
	s_nop 0
	global_load_lds_dwordx4 v[172:173], off
	v_lshl_add_u64 v[172:173], v[236:237], 0, s[92:93]
	s_mov_b32 m0, s23
	s_nop 0
	global_load_lds_dwordx4 v[172:173], off
	s_waitcnt vmcnt(8)
	s_waitcnt lgkmcnt(0)
	s_setprio 1
	s_barrier
	v_mfma_f32_16x16x32_bf16 v[62:65], v[130:133], v[190:193], v[62:65]
	v_mfma_f32_16x16x32_bf16 v[58:61], v[138:141], v[190:193], v[58:61]
	v_mfma_f32_16x16x32_bf16 v[46:49], v[130:133], v[206:209], v[46:49]
	v_mfma_f32_16x16x32_bf16 v[42:45], v[138:141], v[206:209], v[42:45]
	v_mfma_f32_16x16x32_bf16 v[30:33], v[130:133], v[214:217], v[30:33]
	v_mfma_f32_16x16x32_bf16 v[26:29], v[138:141], v[214:217], v[26:29]
	v_mfma_f32_16x16x32_bf16 v[14:17], v[130:133], v[222:225], v[14:17]
	v_mfma_f32_16x16x32_bf16 v[10:13], v[138:141], v[222:225], v[10:13]
	v_mfma_f32_16x16x32_bf16 v[62:65], v[134:137], v[194:197], v[62:65]
	v_mfma_f32_16x16x32_bf16 v[58:61], v[142:145], v[194:197], v[58:61]
	v_mfma_f32_16x16x32_bf16 v[46:49], v[134:137], v[210:213], v[46:49]
	v_mfma_f32_16x16x32_bf16 v[42:45], v[142:145], v[210:213], v[42:45]
	v_mfma_f32_16x16x32_bf16 v[30:33], v[134:137], v[218:221], v[30:33]
	v_mfma_f32_16x16x32_bf16 v[26:29], v[142:145], v[218:221], v[26:29]
	v_mfma_f32_16x16x32_bf16 v[14:17], v[134:137], v[226:229], v[14:17]
	v_mfma_f32_16x16x32_bf16 v[10:13], v[142:145], v[226:229], v[10:13]
	v_mfma_f32_16x16x32_bf16 v[54:57], v[146:149], v[190:193], v[54:57]
	v_mfma_f32_16x16x32_bf16 v[50:53], v[182:185], v[190:193], v[50:53]
	v_mfma_f32_16x16x32_bf16 v[38:41], v[146:149], v[206:209], v[38:41]
	v_mfma_f32_16x16x32_bf16 v[34:37], v[182:185], v[206:209], v[34:37]
	v_mfma_f32_16x16x32_bf16 v[22:25], v[146:149], v[214:217], v[22:25]
	v_mfma_f32_16x16x32_bf16 v[18:21], v[182:185], v[214:217], v[18:21]
	v_mfma_f32_16x16x32_bf16 v[6:9], v[146:149], v[222:225], v[6:9]
	v_mfma_f32_16x16x32_bf16 v[2:5], v[182:185], v[222:225], v[2:5]
	v_mfma_f32_16x16x32_bf16 v[54:57], v[150:153], v[194:197], v[54:57]
	v_mfma_f32_16x16x32_bf16 v[50:53], v[186:189], v[194:197], v[50:53]
	v_mfma_f32_16x16x32_bf16 v[38:41], v[150:153], v[210:213], v[38:41]
	v_mfma_f32_16x16x32_bf16 v[34:37], v[186:189], v[210:213], v[34:37]
	v_mfma_f32_16x16x32_bf16 v[22:25], v[150:153], v[218:221], v[22:25]
	v_mfma_f32_16x16x32_bf16 v[18:21], v[186:189], v[218:221], v[18:21]
	v_mfma_f32_16x16x32_bf16 v[6:9], v[150:153], v[226:229], v[6:9]
	v_mfma_f32_16x16x32_bf16 v[2:5], v[186:189], v[226:229], v[2:5]
	s_barrier
	s_setprio 0
	s_add_u32 s46, s46, 0x100
	s_addc_u32 s47, s47, 0
	s_add_u32 s13, s13, 0x100
	s_addc_u32 s24, s24, 0
	s_cmp_ge_u32 s78, s65
	s_mov_b32 s72, s78
	s_cbranch_scc0 .LBB0_398

; #define PG8_STAGE(bufoff, gbase, voff) do { _Pragma("unroll") for (int _i = 0; _i < 2; ++_i) \
;         __builtin_amdgcn_global_load_lds((const unsigned*)((const char*)(gbase) + (voff)[_i]), (PG8_LAS unsigned*)(lds + (bufoff) + ldsw + _i * 8192), 16, 0, 0); } while (0)
; #define PG8_LDA(dst, b, h) do { _Pragma("unroll") for (int m = 0; m < 4; ++m) _Pragma("unroll") for (int k = 0; k < 2; ++k) dst[m][k] = *(const PG8_LAS bf16x8*)(lds + PG8_SA(b, h) + aoff + m * 2048 + k * 1024); } while (0)
; #define PG8_LDB(dst, b, h) do { _Pragma("unroll") for (int n = 0; n < 2; ++n) _Pragma("unroll") for (int k = 0; k < 2; ++k) dst[n][k] = *(const PG8_LAS bf16x8*)(lds + PG8_SB(b, h) + boff + n * 2048 + k * 1024); } while (0)
; #define PG8_WAIT_V(n) asm volatile("s_waitcnt vmcnt(" #n ")" ::: "memory")
; #define PG8_WAIT_L(n) asm volatile("s_waitcnt lgkmcnt(" #n ")" ::: "memory")
; #define PG8_BAR __builtin_amdgcn_s_barrier()
; #define PG8_SCHED __builtin_amdgcn_sched_barrier(0)
; template <class Epi, class Sched, bool ALIGN_EPI = false, bool SP2 = false, bool F16 = false>
; __device__ __forceinline__ void gemm_phase(PG8_LAS unsigned char* lds, const Gemm g, const Sched& S, const Epi& E) {
;     ...
;         for (int t = 0; t < nt; t += 2) {
;             const bool last = (t == nt - 2);
;             const char* a1 = cA + (size_t)(t + 1) * kstep;
;             const char* a2 = last ? nA : cA + (size_t)(t + 2) * kstep; const char* b2 = last ? nB : cB + (size_t)(t + 2) * kstep;
;             const char* a3 = a2 + kstep; const char* b3 = b2 + kstep;
;             if (last && has_next) S.a_ready(nxt);
;             if constexpr (SP2) {
;             PG8_LDB(B0, 0, 0); PG8_LDB(B1, 0, 1); PG8_SCHED; PG8_LDA(At, 0, 0); PG8_STAGE(PG8_SA(1, 1), a1 + hstepA, voffA);
;             PG8_WAIT_V(8); PG8_WAIT_L(0); PG8_BAR; PG8_MMA(0, 0, At, B0); PG8_MMA(0, 1, At, B1); PG8_BAR; PG8_SCHED;
;             PG8_LDA(At, 0, 1); PG8_STAGE(PG8_SB(0, 0), b2, voffB); PG8_STAGE(PG8_SB(0, 1), b2 + hstepB, voffB); PG8_STAGE(PG8_SA(0, 0), a2, voffA);
;             PG8_WAIT_V(8); PG8_WAIT_L(0); PG8_BAR; PG8_MMA(1, 0, At, B0); PG8_MMA(1, 1, At, B1); PG8_BAR; PG8_SCHED;
.LBB0_564:
	s_add_i32 s73, s52, 2
	s_add_u32 s82, s44, 0x80
	s_addc_u32 s53, s45, 0
	s_add_i32 s94, 0, 0x10000
	s_cmp_eq_u32 s74, s52
	s_cselect_b32 s53, s79, s53
	s_cselect_b32 s52, s78, s82
	s_cselect_b32 s83, s55, s72
	s_cselect_b32 s82, s54, s24
	s_add_i32 s95, 0, 0x14000
	v_add_u32_e32 v142, s94, v163
	v_add_u32_e32 v172, s95, v163
	ds_read_b128 v[130:133], v142
	ds_read_b128 v[134:137], v142 offset:1024
	ds_read_b128 v[138:141], v142 offset:2048
	ds_read_b128 v[142:145], v142 offset:3072
	ds_read_b128 v[146:149], v172
	ds_read_b128 v[150:153], v172 offset:1024
	ds_read_b128 v[182:185], v172 offset:2048
	ds_read_b128 v[186:189], v172 offset:3072
	v_lshl_add_u64 v[172:173], s[44:45], 0, v[168:169]
	s_add_i32 m0, s35, 0xc000
	ds_read_b128 v[190:193], v204
	ds_read_b128 v[194:197], v204 offset:1024
	ds_read_b128 v[206:209], v204 offset:2048
	ds_read_b128 v[210:213], v204 offset:3072
	ds_read_b128 v[214:217], v204 offset:4096
	ds_read_b128 v[218:221], v204 offset:5120
	ds_read_b128 v[222:225], v204 offset:6144
	ds_read_b128 v[226:229], v204 offset:7168
	global_load_lds_dwordx4 v[172:173], off
	v_lshl_add_u64 v[172:173], s[44:45], 0, v[170:171]
	s_add_i32 m0, s35, 0xe000
	s_nop 0
	global_load_lds_dwordx4 v[172:173], off
	s_waitcnt vmcnt(8)
	s_waitcnt lgkmcnt(0)
	s_setprio 1
	s_barrier
	v_mfma_f32_16x16x32_f16 v[122:125], v[130:133], v[190:193], v[122:125]
	v_mfma_f32_16x16x32_f16 v[126:129], v[138:141], v[190:193], v[126:129]
	v_mfma_f32_16x16x32_f16 v[110:113], v[130:133], v[206:209], v[110:113]
	v_mfma_f32_16x16x32_f16 v[106:109], v[138:141], v[206:209], v[106:109]
	v_mfma_f32_16x16x32_f16 v[94:97], v[130:133], v[214:217], v[94:97]
	v_mfma_f32_16x16x32_f16 v[90:93], v[138:141], v[214:217], v[90:93]
	v_mfma_f32_16x16x32_f16 v[78:81], v[130:133], v[222:225], v[78:81]
	v_mfma_f32_16x16x32_f16 v[74:77], v[138:141], v[222:225], v[74:77]
	v_mfma_f32_16x16x32_f16 v[122:125], v[134:137], v[194:197], v[122:125]
	v_mfma_f32_16x16x32_f16 v[126:129], v[142:145], v[194:197], v[126:129]
	v_mfma_f32_16x16x32_f16 v[110:113], v[134:137], v[210:213], v[110:113]
	v_mfma_f32_16x16x32_f16 v[106:109], v[142:145], v[210:213], v[106:109]
	v_mfma_f32_16x16x32_f16 v[94:97], v[134:137], v[218:221], v[94:97]
	v_mfma_f32_16x16x32_f16 v[90:93], v[142:145], v[218:221], v[90:93]
	v_mfma_f32_16x16x32_f16 v[78:81], v[134:137], v[226:229], v[78:81]
	v_mfma_f32_16x16x32_f16 v[74:77], v[142:145], v[226:229], v[74:77]
	v_mfma_f32_16x16x32_f16 v[118:121], v[146:149], v[190:193], v[118:121]
	v_mfma_f32_16x16x32_f16 v[114:117], v[182:185], v[190:193], v[114:117]
	v_mfma_f32_16x16x32_f16 v[102:105], v[146:149], v[206:209], v[102:105]
	v_mfma_f32_16x16x32_f16 v[98:101], v[182:185], v[206:209], v[98:101]
	v_mfma_f32_16x16x32_f16 v[86:89], v[146:149], v[214:217], v[86:89]
	v_mfma_f32_16x16x32_f16 v[82:85], v[182:185], v[214:217], v[82:85]
	v_mfma_f32_16x16x32_f16 v[70:73], v[146:149], v[222:225], v[70:73]
	v_mfma_f32_16x16x32_f16 v[66:69], v[182:185], v[222:225], v[66:69]
	v_mfma_f32_16x16x32_f16 v[118:121], v[150:153], v[194:197], v[118:121]
	v_mfma_f32_16x16x32_f16 v[114:117], v[186:189], v[194:197], v[114:117]
	v_mfma_f32_16x16x32_f16 v[102:105], v[150:153], v[210:213], v[102:105]
	v_mfma_f32_16x16x32_f16 v[98:101], v[186:189], v[210:213], v[98:101]
	v_mfma_f32_16x16x32_f16 v[86:89], v[150:153], v[218:221], v[86:89]
	v_mfma_f32_16x16x32_f16 v[82:85], v[186:189], v[218:221], v[82:85]
	v_mfma_f32_16x16x32_f16 v[70:73], v[150:153], v[226:229], v[70:73]
	v_mfma_f32_16x16x32_f16 v[66:69], v[186:189], v[226:229], v[66:69]
	s_barrier
	s_setprio 0
	s_add_i32 s94, s94, s75
	v_lshl_add_u64 v[172:173], s[82:83], 0, v[156:157]
	s_mov_b32 m0, s94
	ds_read_b128 v[190:193], v204 offset:16384
	ds_read_b128 v[194:197], v204 offset:17408
	ds_read_b128 v[206:209], v204 offset:18432
	ds_read_b128 v[210:213], v204 offset:19456
	ds_read_b128 v[214:217], v204 offset:20480
	ds_read_b128 v[218:221], v204 offset:21504
	ds_read_b128 v[222:225], v204 offset:22528
	ds_read_b128 v[226:229], v204 offset:23552
	global_load_lds_dwordx4 v[172:173], off
	s_add_i32 m0, s94, 0x2000
	v_lshl_add_u64 v[176:177], s[82:83], 0, v[160:161]
	s_add_u32 s82, s82, s48
	s_addc_u32 s83, s83, 0
	s_add_i32 s94, s95, s75
	global_load_lds_dwordx4 v[176:177], off
	v_lshl_add_u64 v[230:231], s[82:83], 0, v[156:157]
	s_mov_b32 m0, s94
	v_lshl_add_u64 v[232:233], s[82:83], 0, v[160:161]
	global_load_lds_dwordx4 v[230:231], off
	s_add_i32 m0, s94, 0x2000
	v_lshl_add_u64 v[234:235], s[52:53], 0, v[154:155]
	global_load_lds_dwordx4 v[232:233], off
	s_mov_b32 m0, s35
	v_lshl_add_u64 v[236:237], s[52:53], 0, v[158:159]
	global_load_lds_dwordx4 v[234:235], off
	s_mov_b32 m0, s2
	s_nop 0
	global_load_lds_dwordx4 v[236:237], off
	s_waitcnt vmcnt(8)
	s_waitcnt lgkmcnt(0)
	s_setprio 1
	s_barrier
; #define PG8_STAGE(bufoff, gbase, voff) do { _Pragma("unroll") for (int _i = 0; _i < 2; ++_i) \
;         __builtin_amdgcn_global_load_lds((const unsigned*)((const char*)(gbase) + (voff)[_i]), (PG8_LAS unsigned*)(lds + (bufoff) + ldsw + _i * 8192), 16, 0, 0); } while (0)
; #define PG8_LDA(dst, b, h) do { _Pragma("unroll") for (int m = 0; m < 4; ++m) _Pragma("unroll") for (int k = 0; k < 2; ++k) dst[m][k] = *(const PG8_LAS bf16x8*)(lds + PG8_SA(b, h) + aoff + m * 2048 + k * 1024); } while (0)
; #define PG8_LDB(dst, b, h) do { _Pragma("unroll") for (int n = 0; n < 2; ++n) _Pragma("unroll") for (int k = 0; k < 2; ++k) dst[n][k] = *(const PG8_LAS bf16x8*)(lds + PG8_SB(b, h) + boff + n * 2048 + k * 1024); } while (0)
; #define PG8_WAIT_V(n) asm volatile("s_waitcnt vmcnt(" #n ")" ::: "memory")
; #define PG8_WAIT_L(n) asm volatile("s_waitcnt lgkmcnt(" #n ")" ::: "memory")
; #define PG8_BAR __builtin_amdgcn_s_barrier()
; #define PG8_SCHED __builtin_amdgcn_sched_barrier(0)
; template <class Epi, class Sched, bool ALIGN_EPI = false, bool SP2 = false, bool F16 = false>
; __device__ __forceinline__ void gemm_phase(PG8_LAS unsigned char* lds, const Gemm g, const Sched& S, const Epi& E) {
;     ...
;             PG8_WAIT_V(8); PG8_WAIT_L(0); PG8_BAR; PG8_MMA(1, 0, At, B0); PG8_MMA(1, 1, At, B1); PG8_BAR; PG8_SCHED;
;             PG8_LDB(B0, 1, 0); PG8_LDB(B1, 1, 1); PG8_SCHED; PG8_LDA(At, 1, 0); PG8_STAGE(PG8_SA(0, 1), a2 + hstepA, voffA);
;             PG8_WAIT_V(8); PG8_WAIT_L(0); PG8_BAR; PG8_MMA(0, 0, At, B0); PG8_MMA(0, 1, At, B1); PG8_BAR; PG8_SCHED;
	v_mfma_f32_16x16x32_f16 v[62:65], v[130:133], v[190:193], v[62:65]
	v_mfma_f32_16x16x32_f16 v[58:61], v[138:141], v[190:193], v[58:61]
	v_mfma_f32_16x16x32_f16 v[46:49], v[130:133], v[206:209], v[46:49]
	v_mfma_f32_16x16x32_f16 v[42:45], v[138:141], v[206:209], v[42:45]
	v_mfma_f32_16x16x32_f16 v[30:33], v[130:133], v[214:217], v[30:33]
	v_mfma_f32_16x16x32_f16 v[26:29], v[138:141], v[214:217], v[26:29]
	v_mfma_f32_16x16x32_f16 v[14:17], v[130:133], v[222:225], v[14:17]
	v_mfma_f32_16x16x32_f16 v[10:13], v[138:141], v[222:225], v[10:13]
	v_mfma_f32_16x16x32_f16 v[62:65], v[134:137], v[194:197], v[62:65]
	v_mfma_f32_16x16x32_f16 v[58:61], v[142:145], v[194:197], v[58:61]
	v_mfma_f32_16x16x32_f16 v[46:49], v[134:137], v[210:213], v[46:49]
	v_mfma_f32_16x16x32_f16 v[42:45], v[142:145], v[210:213], v[42:45]
	v_mfma_f32_16x16x32_f16 v[30:33], v[134:137], v[218:221], v[30:33]
	v_mfma_f32_16x16x32_f16 v[26:29], v[142:145], v[218:221], v[26:29]
	v_mfma_f32_16x16x32_f16 v[14:17], v[134:137], v[226:229], v[14:17]
	v_mfma_f32_16x16x32_f16 v[10:13], v[142:145], v[226:229], v[10:13]
	v_mfma_f32_16x16x32_f16 v[54:57], v[146:149], v[190:193], v[54:57]
	v_mfma_f32_16x16x32_f16 v[50:53], v[182:185], v[190:193], v[50:53]
	v_mfma_f32_16x16x32_f16 v[38:41], v[146:149], v[206:209], v[38:41]
	v_mfma_f32_16x16x32_f16 v[34:37], v[182:185], v[206:209], v[34:37]
	v_mfma_f32_16x16x32_f16 v[22:25], v[146:149], v[214:217], v[22:25]
	v_mfma_f32_16x16x32_f16 v[18:21], v[182:185], v[214:217], v[18:21]
	v_mfma_f32_16x16x32_f16 v[6:9], v[146:149], v[222:225], v[6:9]
	v_mfma_f32_16x16x32_f16 v[2:5], v[182:185], v[222:225], v[2:5]
	v_mfma_f32_16x16x32_f16 v[54:57], v[150:153], v[194:197], v[54:57]
	v_mfma_f32_16x16x32_f16 v[50:53], v[186:189], v[194:197], v[50:53]
	v_mfma_f32_16x16x32_f16 v[38:41], v[150:153], v[210:213], v[38:41]
	v_mfma_f32_16x16x32_f16 v[34:37], v[186:189], v[210:213], v[34:37]
	v_mfma_f32_16x16x32_f16 v[22:25], v[150:153], v[218:221], v[22:25]
	v_mfma_f32_16x16x32_f16 v[18:21], v[186:189], v[218:221], v[18:21]
	v_mfma_f32_16x16x32_f16 v[6:9], v[150:153], v[226:229], v[6:9]
	v_mfma_f32_16x16x32_f16 v[2:5], v[186:189], v[226:229], v[2:5]
	s_barrier
	s_setprio 0
	s_add_i32 s82, 0, 0x18000
	s_add_i32 s83, 0, 0x1c000
	v_add_u32_e32 v142, s82, v163
	v_add_u32_e32 v174, s83, v163
	ds_read_b128 v[130:133], v142
	ds_read_b128 v[134:137], v142 offset:1024
	ds_read_b128 v[138:141], v142 offset:2048
	ds_read_b128 v[142:145], v142 offset:3072
	ds_read_b128 v[146:149], v174
	ds_read_b128 v[150:153], v174 offset:1024
	ds_read_b128 v[182:185], v174 offset:2048
	ds_read_b128 v[186:189], v174 offset:3072
	s_add_u32 s52, s52, s8
	s_addc_u32 s53, s53, 0
	s_mov_b32 m0, s22
	v_lshl_add_u64 v[238:239], s[52:53], 0, v[154:155]
	ds_read_b128 v[190:193], v204 offset:32768
	ds_read_b128 v[194:197], v204 offset:33792
	ds_read_b128 v[206:209], v204 offset:34816
	ds_read_b128 v[210:213], v204 offset:35840
	ds_read_b128 v[214:217], v204 offset:36864
	ds_read_b128 v[218:221], v204 offset:37888
	ds_read_b128 v[222:225], v204 offset:38912
	ds_read_b128 v[226:229], v204 offset:39936
	global_load_lds_dwordx4 v[238:239], off
	v_lshl_add_u64 v[238:239], s[52:53], 0, v[158:159]
	s_mov_b32 m0, s23
	s_nop 0
	global_load_lds_dwordx4 v[238:239], off
	s_waitcnt vmcnt(8)
	s_waitcnt lgkmcnt(0)
	s_setprio 1
	s_barrier
	v_mfma_f32_16x16x32_f16 v[122:125], v[130:133], v[190:193], v[122:125]
	v_mfma_f32_16x16x32_f16 v[126:129], v[138:141], v[190:193], v[126:129]
	v_mfma_f32_16x16x32_f16 v[110:113], v[130:133], v[206:209], v[110:113]
	v_mfma_f32_16x16x32_f16 v[106:109], v[138:141], v[206:209], v[106:109]
	v_mfma_f32_16x16x32_f16 v[94:97], v[130:133], v[214:217], v[94:97]
	v_mfma_f32_16x16x32_f16 v[90:93], v[138:141], v[214:217], v[90:93]
	v_mfma_f32_16x16x32_f16 v[78:81], v[130:133], v[222:225], v[78:81]
	v_mfma_f32_16x16x32_f16 v[74:77], v[138:141], v[222:225], v[74:77]
	v_mfma_f32_16x16x32_f16 v[122:125], v[134:137], v[194:197], v[122:125]
	v_mfma_f32_16x16x32_f16 v[126:129], v[142:145], v[194:197], v[126:129]
	v_mfma_f32_16x16x32_f16 v[110:113], v[134:137], v[210:213], v[110:113]
	v_mfma_f32_16x16x32_f16 v[106:109], v[142:145], v[210:213], v[106:109]
	v_mfma_f32_16x16x32_f16 v[94:97], v[134:137], v[218:221], v[94:97]
	v_mfma_f32_16x16x32_f16 v[90:93], v[142:145], v[218:221], v[90:93]
	v_mfma_f32_16x16x32_f16 v[78:81], v[134:137], v[226:229], v[78:81]
	v_mfma_f32_16x16x32_f16 v[74:77], v[142:145], v[226:229], v[74:77]
	v_mfma_f32_16x16x32_f16 v[118:121], v[146:149], v[190:193], v[118:121]
	v_mfma_f32_16x16x32_f16 v[114:117], v[182:185], v[190:193], v[114:117]
	v_mfma_f32_16x16x32_f16 v[102:105], v[146:149], v[206:209], v[102:105]
	v_mfma_f32_16x16x32_f16 v[98:101], v[182:185], v[206:209], v[98:101]
	v_mfma_f32_16x16x32_f16 v[86:89], v[146:149], v[214:217], v[86:89]
	v_mfma_f32_16x16x32_f16 v[82:85], v[182:185], v[214:217], v[82:85]
	v_mfma_f32_16x16x32_f16 v[70:73], v[146:149], v[222:225], v[70:73]
	v_mfma_f32_16x16x32_f16 v[66:69], v[182:185], v[222:225], v[66:69]
	v_mfma_f32_16x16x32_f16 v[118:121], v[150:153], v[194:197], v[118:121]
	v_mfma_f32_16x16x32_f16 v[114:117], v[186:189], v[194:197], v[114:117]
	v_mfma_f32_16x16x32_f16 v[102:105], v[150:153], v[210:213], v[102:105]
	v_mfma_f32_16x16x32_f16 v[98:101], v[186:189], v[210:213], v[98:101]
	v_mfma_f32_16x16x32_f16 v[86:89], v[150:153], v[218:221], v[86:89]
	v_mfma_f32_16x16x32_f16 v[82:85], v[186:189], v[218:221], v[82:85]
	v_mfma_f32_16x16x32_f16 v[70:73], v[150:153], v[226:229], v[70:73]
	v_mfma_f32_16x16x32_f16 v[66:69], v[186:189], v[226:229], v[66:69]
	s_barrier
; #define PG8_STAGE(bufoff, gbase, voff) do { _Pragma("unroll") for (int _i = 0; _i < 2; ++_i) \
;         __builtin_amdgcn_global_load_lds((const unsigned*)((const char*)(gbase) + (voff)[_i]), (PG8_LAS unsigned*)(lds + (bufoff) + ldsw + _i * 8192), 16, 0, 0); } while (0)
; #define PG8_LDA(dst, b, h) do { _Pragma("unroll") for (int m = 0; m < 4; ++m) _Pragma("unroll") for (int k = 0; k < 2; ++k) dst[m][k] = *(const PG8_LAS bf16x8*)(lds + PG8_SA(b, h) + aoff + m * 2048 + k * 1024); } while (0)
; #define PG8_WAIT_V(n) asm volatile("s_waitcnt vmcnt(" #n ")" ::: "memory")
; #define PG8_WAIT_L(n) asm volatile("s_waitcnt lgkmcnt(" #n ")" ::: "memory")
; #define PG8_BAR __builtin_amdgcn_s_barrier()
; #define PG8_SCHED __builtin_amdgcn_sched_barrier(0)
; template <class Epi, class Sched, bool ALIGN_EPI = false, bool SP2 = false, bool F16 = false>
; __device__ __forceinline__ void gemm_phase(PG8_LAS unsigned char* lds, const Gemm g, const Sched& S, const Epi& E) {
;     ...
;             PG8_LDA(At, 1, 1); PG8_STAGE(PG8_SB(1, 0), b3, voffB); PG8_STAGE(PG8_SB(1, 1), b3 + hstepB, voffB); PG8_STAGE(PG8_SA(1, 0), a3, voffA);
;             PG8_WAIT_V(8); PG8_WAIT_L(0); PG8_BAR; PG8_MMA(1, 0, At, B0); PG8_MMA(1, 1, At, B1); PG8_BAR; PG8_SCHED;
	s_setprio 0
	s_add_i32 s52, s82, s75
	v_lshl_add_u64 v[172:173], v[172:173], 0, s[92:93]
	s_mov_b32 m0, s52
	ds_read_b128 v[190:193], v204 offset:49152
	ds_read_b128 v[194:197], v204 offset:50176
	ds_read_b128 v[206:209], v204 offset:51200
	ds_read_b128 v[210:213], v204 offset:52224
	ds_read_b128 v[214:217], v204 offset:53248
	ds_read_b128 v[218:221], v204 offset:54272
	ds_read_b128 v[222:225], v204 offset:55296
	ds_read_b128 v[226:229], v204 offset:56320
	global_load_lds_dwordx4 v[172:173], off
	v_lshl_add_u64 v[172:173], v[176:177], 0, s[92:93]
	s_add_i32 m0, s52, 0x2000
	s_add_i32 s52, s83, s75
	global_load_lds_dwordx4 v[172:173], off
	v_lshl_add_u64 v[172:173], v[230:231], 0, s[92:93]
	s_mov_b32 m0, s52
	s_nop 0
	global_load_lds_dwordx4 v[172:173], off
	v_lshl_add_u64 v[172:173], v[232:233], 0, s[92:93]
	s_add_i32 m0, s52, 0x2000
	s_nop 0
	global_load_lds_dwordx4 v[172:173], off
	v_lshl_add_u64 v[172:173], v[234:235], 0, s[92:93]
	s_mov_b32 m0, s61
	s_nop 0
	global_load_lds_dwordx4 v[172:173], off
	v_lshl_add_u64 v[172:173], v[236:237], 0, s[92:93]
	s_mov_b32 m0, s18
	s_nop 0
	global_load_lds_dwordx4 v[172:173], off
	s_waitcnt vmcnt(8)
	s_waitcnt lgkmcnt(0)
	s_setprio 1
	s_barrier
	v_mfma_f32_16x16x32_f16 v[62:65], v[130:133], v[190:193], v[62:65]
	v_mfma_f32_16x16x32_f16 v[58:61], v[138:141], v[190:193], v[58:61]
	v_mfma_f32_16x16x32_f16 v[46:49], v[130:133], v[206:209], v[46:49]
	v_mfma_f32_16x16x32_f16 v[42:45], v[138:141], v[206:209], v[42:45]
	v_mfma_f32_16x16x32_f16 v[30:33], v[130:133], v[214:217], v[30:33]
	v_mfma_f32_16x16x32_f16 v[26:29], v[138:141], v[214:217], v[26:29]
	v_mfma_f32_16x16x32_f16 v[14:17], v[130:133], v[222:225], v[14:17]
	v_mfma_f32_16x16x32_f16 v[10:13], v[138:141], v[222:225], v[10:13]
	v_mfma_f32_16x16x32_f16 v[62:65], v[134:137], v[194:197], v[62:65]
	v_mfma_f32_16x16x32_f16 v[58:61], v[142:145], v[194:197], v[58:61]
	v_mfma_f32_16x16x32_f16 v[46:49], v[134:137], v[210:213], v[46:49]
	v_mfma_f32_16x16x32_f16 v[42:45], v[142:145], v[210:213], v[42:45]
	v_mfma_f32_16x16x32_f16 v[30:33], v[134:137], v[218:221], v[30:33]
	v_mfma_f32_16x16x32_f16 v[26:29], v[142:145], v[218:221], v[26:29]
	v_mfma_f32_16x16x32_f16 v[14:17], v[134:137], v[226:229], v[14:17]
	v_mfma_f32_16x16x32_f16 v[10:13], v[142:145], v[226:229], v[10:13]
	v_mfma_f32_16x16x32_f16 v[54:57], v[146:149], v[190:193], v[54:57]
	v_mfma_f32_16x16x32_f16 v[50:53], v[182:185], v[190:193], v[50:53]
	v_mfma_f32_16x16x32_f16 v[38:41], v[146:149], v[206:209], v[38:41]
	v_mfma_f32_16x16x32_f16 v[34:37], v[182:185], v[206:209], v[34:37]
	v_mfma_f32_16x16x32_f16 v[22:25], v[146:149], v[214:217], v[22:25]
	v_mfma_f32_16x16x32_f16 v[18:21], v[182:185], v[214:217], v[18:21]
	v_mfma_f32_16x16x32_f16 v[6:9], v[146:149], v[222:225], v[6:9]
	v_mfma_f32_16x16x32_f16 v[2:5], v[182:185], v[222:225], v[2:5]
	v_mfma_f32_16x16x32_f16 v[54:57], v[150:153], v[194:197], v[54:57]
	v_mfma_f32_16x16x32_f16 v[50:53], v[186:189], v[194:197], v[50:53]
	v_mfma_f32_16x16x32_f16 v[38:41], v[150:153], v[210:213], v[38:41]
	v_mfma_f32_16x16x32_f16 v[34:37], v[186:189], v[210:213], v[34:37]
	v_mfma_f32_16x16x32_f16 v[22:25], v[150:153], v[218:221], v[22:25]
	v_mfma_f32_16x16x32_f16 v[18:21], v[186:189], v[218:221], v[18:21]
	v_mfma_f32_16x16x32_f16 v[6:9], v[150:153], v[226:229], v[6:9]
	v_mfma_f32_16x16x32_f16 v[2:5], v[186:189], v[226:229], v[2:5]
	s_barrier
	s_setprio 0
	s_add_u32 s44, s44, 0x100
	s_addc_u32 s45, s45, 0
	s_add_u32 s24, s24, 0x100
	s_addc_u32 s72, s72, 0
	s_cmp_ge_u32 s73, s65
	s_mov_b32 s52, s73
	s_cbranch_scc0 .LBB0_564
